# merge epilogue: redundant NaN-canonicalising v_max before the clamp dropped (bit-identical)
# speedup vs baseline: 1.0057x; 1.0057x over previous
; __device__ __forceinline__ unsigned pk2(float lo, float hi) { f32x2_t v = {lo, hi}; bf16x2_t b = __builtin_convertvector(v, bf16x2_t); return __builtin_bit_cast(unsigned, b); }
;     static __device__ __forceinline__ float e1(float x) { return 1.0f + __expf(-fminf(fmaxf(x, -60.f), 60.f)); }
;     __device__ __forceinline__ void operator()(f32x4 (&acc)[2][2][4][2], const Unit& u, int wr, int wc, int fr, int fq) const {
;         const int row0 = u.pm * BM + wr * 64 + fr, col0 = u.pn * BM + wc * 32 + 8 * fq;
; #pragma unroll
;         for (int ai = 0; ai < 2; ++ai)
; #pragma unroll
;             for (int m = 0; m < 4; ++m) {
;                 const int row = row0 + ai * HALF + m * 16;
; #pragma unroll
;                 for (int bj = 0; bj < 2; ++bj) {
;                     const int col = col0 + bj * HALF;
;                     const bf16_t* gp = proj + (size_t)row * NP + C_GATE + u.z * D + col;
;                     const u32x4 ga = *(const u32x4*)gp;
;                     float sc[8];
;                     { float a[8]; unpack8(ga, a);
; #pragma unroll
;                       for (int j = 0; j < 8; ++j) sc[j] = __builtin_amdgcn_rcpf(e1(a[j])); }
;                     if (u.z < 2) { const u32x4 gb = *(const u32x4*)(gp + D); float b[8]; unpack8(gb, b);
; #pragma unroll
;                       for (int j = 0; j < 8; ++j) sc[j] *= e1(b[j]); }
;                     f32x4 v0 = acc[ai][bj][m][0], v1 = acc[ai][bj][m][1];
;                     v0[0] *= sc[0]; v0[1] *= sc[1]; v0[2] *= sc[2]; v0[3] *= sc[3]; v1[0] *= sc[4]; v1[1] *= sc[5]; v1[2] *= sc[6]; v1[3] *= sc[7];
;                     if (u.z < 2) { acc[ai][bj][m][0] = v0; acc[ai][bj][m][1] = v1; }
;                     else { u32x4 w; w.x = pk2(v0[0], v0[1]); w.y = pk2(v0[2], v0[3]); w.z = pk2(v1[0], v1[1]); w.w = pk2(v1[2], v1[3]); *(u32x4*)(YB + (size_t)row * D + col) = w; }
.LBB0_622:
	v_lshl_add_u32 v152, s6, 8, v158
	v_lshl_or_b32 v2, s5, 8, v160
	v_mov_b64_e32 v[132:133], s[46:47]
	s_lshl_b32 s62, s4, 12
	s_add_u32 s62, s62, 0x6800
	s_mov_b32 s63, 0
	v_mad_i64_i32 v[132:133], s[6:7], v152, s25, v[132:133]
	v_ashrrev_i32_e32 v3, 31, v2
	v_lshl_add_u64 v[132:133], v[132:133], 0, s[62:63]
	v_ashrrev_i32_e32 v153, 31, v152
	v_lshlrev_b64 v[134:135], 12, v[152:153]
	v_lshl_add_u64 v[154:155], s[48:49], 0, v[134:135]
	v_lshl_add_u64 v[154:155], v[2:3], 1, v[154:155]
	v_lshl_add_u64 v[152:153], v[2:3], 1, v[132:133]
	s_cmp_lt_i32 s4, 2
	s_cbranch_scc0 .Lp3_store
	s_mov_b64 s[8:9], 0x0
	v_lshl_add_u64 v[156:157], v[152:153], 0, s[8:9]
	global_load_dwordx4 v[162:165], v[156:157], off offset:-4096
	global_load_dwordx4 v[166:169], v[156:157], off offset:0
	s_mov_b64 s[8:9], 0x0
	v_lshl_add_u64 v[156:157], v[152:153], 0, s[8:9]
	global_load_dwordx4 v[170:173], v[156:157], off offset:-3840
	global_load_dwordx4 v[174:177], v[156:157], off offset:256
	s_mov_b64 s[8:9], 0x88000
	v_lshl_add_u64 v[156:157], v[152:153], 0, s[8:9]
	global_load_dwordx4 v[178:181], v[156:157], off offset:-4096
	global_load_dwordx4 v[182:185], v[156:157], off offset:0
	s_mov_b64 s[8:9], 0x88000
	v_lshl_add_u64 v[156:157], v[152:153], 0, s[8:9]
	global_load_dwordx4 v[186:189], v[156:157], off offset:-3840
	global_load_dwordx4 v[190:193], v[156:157], off offset:256
	s_mov_b64 s[8:9], 0x110000
	v_lshl_add_u64 v[156:157], v[152:153], 0, s[8:9]
	global_load_dwordx4 v[194:197], v[156:157], off offset:-4096
	global_load_dwordx4 v[198:201], v[156:157], off offset:0
	s_mov_b64 s[8:9], 0x110000
	v_lshl_add_u64 v[156:157], v[152:153], 0, s[8:9]
	global_load_dwordx4 v[206:209], v[156:157], off offset:-3840
	global_load_dwordx4 v[210:213], v[156:157], off offset:256
	s_mov_b64 s[8:9], 0x198000
	v_lshl_add_u64 v[156:157], v[152:153], 0, s[8:9]
	global_load_dwordx4 v[228:231], v[156:157], off offset:-4096
	global_load_dwordx4 v[232:235], v[156:157], off offset:0
	s_mov_b64 s[8:9], 0x198000
	v_lshl_add_u64 v[156:157], v[152:153], 0, s[8:9]
	global_load_dwordx4 v[236:239], v[156:157], off offset:-3840
	global_load_dwordx4 v[240:243], v[156:157], off offset:256
	s_waitcnt vmcnt(14)
	v_lshlrev_b32_e32 v132, 16, v162
	v_and_b32_e32 v133, 0xffff0000, v162
	v_lshlrev_b32_e32 v134, 16, v163
	v_and_b32_e32 v135, 0xffff0000, v163
	v_lshlrev_b32_e32 v136, 16, v164
	v_and_b32_e32 v137, 0xffff0000, v164
	v_lshlrev_b32_e32 v138, 16, v165
	v_and_b32_e32 v139, 0xffff0000, v165
	v_lshlrev_b32_e32 v244, 16, v166
	v_and_b32_e32 v245, 0xffff0000, v166
	v_lshlrev_b32_e32 v246, 16, v167
	v_and_b32_e32 v247, 0xffff0000, v167
	v_lshlrev_b32_e32 v248, 16, v168
	v_and_b32_e32 v249, 0xffff0000, v168
	v_lshlrev_b32_e32 v250, 16, v169
	v_and_b32_e32 v251, 0xffff0000, v169
	s_mov_b64 s[8:9], 0x440000
	v_lshl_add_u64 v[156:157], v[152:153], 0, s[8:9]
	global_load_dwordx4 v[162:165], v[156:157], off offset:-4096
	global_load_dwordx4 v[166:169], v[156:157], off offset:0
	v_med3_f32 v132, v132, s97, v226
	v_med3_f32 v133, v133, s97, v226
	v_med3_f32 v134, v134, s97, v226
	v_med3_f32 v135, v135, s97, v226
	v_med3_f32 v136, v136, s97, v226
	v_med3_f32 v137, v137, s97, v226
	v_med3_f32 v138, v138, s97, v226
	v_med3_f32 v139, v139, s97, v226
	v_mul_f32_e32 v132, 0xbfb8aa3b, v132
	v_mul_f32_e32 v133, 0xbfb8aa3b, v133
	v_mul_f32_e32 v134, 0xbfb8aa3b, v134
	v_mul_f32_e32 v135, 0xbfb8aa3b, v135
	v_mul_f32_e32 v136, 0xbfb8aa3b, v136
	v_mul_f32_e32 v137, 0xbfb8aa3b, v137
	v_mul_f32_e32 v138, 0xbfb8aa3b, v138
	v_mul_f32_e32 v139, 0xbfb8aa3b, v139
	v_exp_f32_e32 v132, v132
	v_exp_f32_e32 v133, v133
	v_exp_f32_e32 v134, v134
	v_exp_f32_e32 v135, v135
	v_exp_f32_e32 v136, v136
	v_exp_f32_e32 v137, v137
	v_exp_f32_e32 v138, v138
	v_exp_f32_e32 v139, v139
	v_add_f32_e32 v132, 1.0, v132
	v_add_f32_e32 v133, 1.0, v133
	v_add_f32_e32 v134, 1.0, v134
	v_add_f32_e32 v135, 1.0, v135
	v_add_f32_e32 v136, 1.0, v136
	v_add_f32_e32 v137, 1.0, v137
	v_add_f32_e32 v138, 1.0, v138
	v_add_f32_e32 v139, 1.0, v139
	v_rcp_f32_e32 v132, v132
	v_rcp_f32_e32 v133, v133
	v_rcp_f32_e32 v134, v134
	v_rcp_f32_e32 v135, v135
	v_rcp_f32_e32 v136, v136
	v_rcp_f32_e32 v137, v137
	v_rcp_f32_e32 v138, v138
	v_rcp_f32_e32 v139, v139
	v_med3_f32 v244, v244, s97, v226
	v_med3_f32 v245, v245, s97, v226
	v_med3_f32 v246, v246, s97, v226
	v_med3_f32 v247, v247, s97, v226
	v_med3_f32 v248, v248, s97, v226
	v_med3_f32 v249, v249, s97, v226
	v_med3_f32 v250, v250, s97, v226
	v_med3_f32 v251, v251, s97, v226
	v_mul_f32_e32 v244, 0xbfb8aa3b, v244
	v_mul_f32_e32 v245, 0xbfb8aa3b, v245
	v_mul_f32_e32 v246, 0xbfb8aa3b, v246
	v_mul_f32_e32 v247, 0xbfb8aa3b, v247
	v_mul_f32_e32 v248, 0xbfb8aa3b, v248
	v_mul_f32_e32 v249, 0xbfb8aa3b, v249
	v_mul_f32_e32 v250, 0xbfb8aa3b, v250
	v_mul_f32_e32 v251, 0xbfb8aa3b, v251
	v_exp_f32_e32 v244, v244
	v_exp_f32_e32 v245, v245
	v_exp_f32_e32 v246, v246
	v_exp_f32_e32 v247, v247
	v_exp_f32_e32 v248, v248
	v_exp_f32_e32 v249, v249
	v_exp_f32_e32 v250, v250
	v_exp_f32_e32 v251, v251
	v_add_f32_e32 v244, 1.0, v244
	v_add_f32_e32 v245, 1.0, v245
	v_add_f32_e32 v246, 1.0, v246
	v_add_f32_e32 v247, 1.0, v247
	v_add_f32_e32 v248, 1.0, v248
	v_add_f32_e32 v249, 1.0, v249
	v_add_f32_e32 v250, 1.0, v250
	v_add_f32_e32 v251, 1.0, v251
	v_pk_mul_f32 v[132:133], v[132:133], v[244:245]
	v_pk_mul_f32 v[134:135], v[134:135], v[246:247]
	v_pk_mul_f32 v[136:137], v[136:137], v[248:249]
	v_pk_mul_f32 v[138:139], v[138:139], v[250:251]
	v_pk_mul_f32 v[128:129], v[128:129], v[132:133]
	v_pk_mul_f32 v[130:131], v[130:131], v[134:135]
	v_pk_mul_f32 v[124:125], v[124:125], v[136:137]
	v_pk_mul_f32 v[126:127], v[126:127], v[138:139]
	s_waitcnt vmcnt(14)
;     static __device__ __forceinline__ float e1(float x) { return 1.0f + __expf(-fminf(fmaxf(x, -60.f), 60.f)); }
;     __device__ __forceinline__ void operator()(f32x4 (&acc)[2][2][4][2], const Unit& u, int wr, int wc, int fr, int fq) const {
;     ...
;                     const int col = col0 + bj * HALF;
;                     const bf16_t* gp = proj + (size_t)row * NP + C_GATE + u.z * D + col;
;                     const u32x4 ga = *(const u32x4*)gp;
;                     float sc[8];
;                     { float a[8]; unpack8(ga, a);
; #pragma unroll
;                       for (int j = 0; j < 8; ++j) sc[j] = __builtin_amdgcn_rcpf(e1(a[j])); }
;                     if (u.z < 2) { const u32x4 gb = *(const u32x4*)(gp + D); float b[8]; unpack8(gb, b);
; #pragma unroll
;                       for (int j = 0; j < 8; ++j) sc[j] *= e1(b[j]); }
;                     f32x4 v0 = acc[ai][bj][m][0], v1 = acc[ai][bj][m][1];
;                     v0[0] *= sc[0]; v0[1] *= sc[1]; v0[2] *= sc[2]; v0[3] *= sc[3]; v1[0] *= sc[4]; v1[1] *= sc[5]; v1[2] *= sc[6]; v1[3] *= sc[7];
;                     if (u.z < 2) { acc[ai][bj][m][0] = v0; acc[ai][bj][m][1] = v1; }
	v_lshlrev_b32_e32 v132, 16, v170
	v_and_b32_e32 v133, 0xffff0000, v170
	v_lshlrev_b32_e32 v134, 16, v171
	v_and_b32_e32 v135, 0xffff0000, v171
	v_lshlrev_b32_e32 v136, 16, v172
	v_and_b32_e32 v137, 0xffff0000, v172
	v_lshlrev_b32_e32 v138, 16, v173
	v_and_b32_e32 v139, 0xffff0000, v173
	v_lshlrev_b32_e32 v244, 16, v174
	v_and_b32_e32 v245, 0xffff0000, v174
	v_lshlrev_b32_e32 v246, 16, v175
	v_and_b32_e32 v247, 0xffff0000, v175
	v_lshlrev_b32_e32 v248, 16, v176
	v_and_b32_e32 v249, 0xffff0000, v176
	v_lshlrev_b32_e32 v250, 16, v177
	v_and_b32_e32 v251, 0xffff0000, v177
	s_mov_b64 s[8:9], 0x440000
	v_lshl_add_u64 v[156:157], v[152:153], 0, s[8:9]
	global_load_dwordx4 v[170:173], v[156:157], off offset:-3840
	global_load_dwordx4 v[174:177], v[156:157], off offset:256
	v_med3_f32 v132, v132, s97, v226
	v_med3_f32 v133, v133, s97, v226
	v_med3_f32 v134, v134, s97, v226
	v_med3_f32 v135, v135, s97, v226
	v_med3_f32 v136, v136, s97, v226
	v_med3_f32 v137, v137, s97, v226
	v_med3_f32 v138, v138, s97, v226
	v_med3_f32 v139, v139, s97, v226
	v_mul_f32_e32 v132, 0xbfb8aa3b, v132
	v_mul_f32_e32 v133, 0xbfb8aa3b, v133
	v_mul_f32_e32 v134, 0xbfb8aa3b, v134
	v_mul_f32_e32 v135, 0xbfb8aa3b, v135
	v_mul_f32_e32 v136, 0xbfb8aa3b, v136
	v_mul_f32_e32 v137, 0xbfb8aa3b, v137
	v_mul_f32_e32 v138, 0xbfb8aa3b, v138
	v_mul_f32_e32 v139, 0xbfb8aa3b, v139
	v_exp_f32_e32 v132, v132
	v_exp_f32_e32 v133, v133
	v_exp_f32_e32 v134, v134
	v_exp_f32_e32 v135, v135
	v_exp_f32_e32 v136, v136
	v_exp_f32_e32 v137, v137
	v_exp_f32_e32 v138, v138
	v_exp_f32_e32 v139, v139
	v_add_f32_e32 v132, 1.0, v132
	v_add_f32_e32 v133, 1.0, v133
	v_add_f32_e32 v134, 1.0, v134
	v_add_f32_e32 v135, 1.0, v135
	v_add_f32_e32 v136, 1.0, v136
	v_add_f32_e32 v137, 1.0, v137
	v_add_f32_e32 v138, 1.0, v138
	v_add_f32_e32 v139, 1.0, v139
	v_rcp_f32_e32 v132, v132
	v_rcp_f32_e32 v133, v133
	v_rcp_f32_e32 v134, v134
	v_rcp_f32_e32 v135, v135
	v_rcp_f32_e32 v136, v136
	v_rcp_f32_e32 v137, v137
	v_rcp_f32_e32 v138, v138
	v_rcp_f32_e32 v139, v139
	v_med3_f32 v244, v244, s97, v226
	v_med3_f32 v245, v245, s97, v226
	v_med3_f32 v246, v246, s97, v226
	v_med3_f32 v247, v247, s97, v226
	v_med3_f32 v248, v248, s97, v226
	v_med3_f32 v249, v249, s97, v226
	v_med3_f32 v250, v250, s97, v226
	v_med3_f32 v251, v251, s97, v226
	v_mul_f32_e32 v244, 0xbfb8aa3b, v244
	v_mul_f32_e32 v245, 0xbfb8aa3b, v245
	v_mul_f32_e32 v246, 0xbfb8aa3b, v246
	v_mul_f32_e32 v247, 0xbfb8aa3b, v247
	v_mul_f32_e32 v248, 0xbfb8aa3b, v248
	v_mul_f32_e32 v249, 0xbfb8aa3b, v249
	v_mul_f32_e32 v250, 0xbfb8aa3b, v250
	v_mul_f32_e32 v251, 0xbfb8aa3b, v251
	v_exp_f32_e32 v244, v244
	v_exp_f32_e32 v245, v245
	v_exp_f32_e32 v246, v246
	v_exp_f32_e32 v247, v247
	v_exp_f32_e32 v248, v248
	v_exp_f32_e32 v249, v249
	v_exp_f32_e32 v250, v250
	v_exp_f32_e32 v251, v251
	v_add_f32_e32 v244, 1.0, v244
	v_add_f32_e32 v245, 1.0, v245
	v_add_f32_e32 v246, 1.0, v246
	v_add_f32_e32 v247, 1.0, v247
	v_add_f32_e32 v248, 1.0, v248
	v_add_f32_e32 v249, 1.0, v249
	v_add_f32_e32 v250, 1.0, v250
	v_add_f32_e32 v251, 1.0, v251
	v_pk_mul_f32 v[132:133], v[132:133], v[244:245]
	v_pk_mul_f32 v[134:135], v[134:135], v[246:247]
	v_pk_mul_f32 v[136:137], v[136:137], v[248:249]
	v_pk_mul_f32 v[138:139], v[138:139], v[250:251]
	v_pk_mul_f32 v[96:97], v[96:97], v[132:133]
	v_pk_mul_f32 v[98:99], v[98:99], v[134:135]
	v_pk_mul_f32 v[92:93], v[92:93], v[136:137]
	v_pk_mul_f32 v[94:95], v[94:95], v[138:139]
	s_waitcnt vmcnt(14)
	v_lshlrev_b32_e32 v132, 16, v178
	v_and_b32_e32 v133, 0xffff0000, v178
	v_lshlrev_b32_e32 v134, 16, v179
	v_and_b32_e32 v135, 0xffff0000, v179
	v_lshlrev_b32_e32 v136, 16, v180
	v_and_b32_e32 v137, 0xffff0000, v180
	v_lshlrev_b32_e32 v138, 16, v181
	v_and_b32_e32 v139, 0xffff0000, v181
	v_lshlrev_b32_e32 v244, 16, v182
	v_and_b32_e32 v245, 0xffff0000, v182
	v_lshlrev_b32_e32 v246, 16, v183
	v_and_b32_e32 v247, 0xffff0000, v183
	v_lshlrev_b32_e32 v248, 16, v184
	v_and_b32_e32 v249, 0xffff0000, v184
	v_lshlrev_b32_e32 v250, 16, v185
	v_and_b32_e32 v251, 0xffff0000, v185
	s_mov_b64 s[8:9], 0x4c8000
	v_lshl_add_u64 v[156:157], v[152:153], 0, s[8:9]
	global_load_dwordx4 v[178:181], v[156:157], off offset:-4096
	global_load_dwordx4 v[182:185], v[156:157], off offset:0
	v_med3_f32 v132, v132, s97, v226
	v_med3_f32 v133, v133, s97, v226
	v_med3_f32 v134, v134, s97, v226
	v_med3_f32 v135, v135, s97, v226
	v_med3_f32 v136, v136, s97, v226
	v_med3_f32 v137, v137, s97, v226
	v_med3_f32 v138, v138, s97, v226
	v_med3_f32 v139, v139, s97, v226
	v_mul_f32_e32 v132, 0xbfb8aa3b, v132
	v_mul_f32_e32 v133, 0xbfb8aa3b, v133
	v_mul_f32_e32 v134, 0xbfb8aa3b, v134
	v_mul_f32_e32 v135, 0xbfb8aa3b, v135
	v_mul_f32_e32 v136, 0xbfb8aa3b, v136
	v_mul_f32_e32 v137, 0xbfb8aa3b, v137
	v_mul_f32_e32 v138, 0xbfb8aa3b, v138
	v_mul_f32_e32 v139, 0xbfb8aa3b, v139
	v_exp_f32_e32 v132, v132
	v_exp_f32_e32 v133, v133
	v_exp_f32_e32 v134, v134
	v_exp_f32_e32 v135, v135
	v_exp_f32_e32 v136, v136
	v_exp_f32_e32 v137, v137
	v_exp_f32_e32 v138, v138
	v_exp_f32_e32 v139, v139
	v_add_f32_e32 v132, 1.0, v132
	v_add_f32_e32 v133, 1.0, v133
	v_add_f32_e32 v134, 1.0, v134
	v_add_f32_e32 v135, 1.0, v135
	v_add_f32_e32 v136, 1.0, v136
	v_add_f32_e32 v137, 1.0, v137
	v_add_f32_e32 v138, 1.0, v138
	v_add_f32_e32 v139, 1.0, v139
	v_rcp_f32_e32 v132, v132
	v_rcp_f32_e32 v133, v133
	v_rcp_f32_e32 v134, v134
	v_rcp_f32_e32 v135, v135
	v_rcp_f32_e32 v136, v136
	v_rcp_f32_e32 v137, v137
	v_rcp_f32_e32 v138, v138
	v_rcp_f32_e32 v139, v139
	v_med3_f32 v244, v244, s97, v226
	v_med3_f32 v245, v245, s97, v226
	v_med3_f32 v246, v246, s97, v226
	v_med3_f32 v247, v247, s97, v226
	v_med3_f32 v248, v248, s97, v226
	v_med3_f32 v249, v249, s97, v226
	v_med3_f32 v250, v250, s97, v226
	v_med3_f32 v251, v251, s97, v226
	v_mul_f32_e32 v244, 0xbfb8aa3b, v244
	v_mul_f32_e32 v245, 0xbfb8aa3b, v245
	v_mul_f32_e32 v246, 0xbfb8aa3b, v246
	v_mul_f32_e32 v247, 0xbfb8aa3b, v247
	v_mul_f32_e32 v248, 0xbfb8aa3b, v248
	v_mul_f32_e32 v249, 0xbfb8aa3b, v249
	v_mul_f32_e32 v250, 0xbfb8aa3b, v250
	v_mul_f32_e32 v251, 0xbfb8aa3b, v251
	v_exp_f32_e32 v244, v244
	v_exp_f32_e32 v245, v245
	v_exp_f32_e32 v246, v246
	v_exp_f32_e32 v247, v247
	v_exp_f32_e32 v248, v248
	v_exp_f32_e32 v249, v249
	v_exp_f32_e32 v250, v250
	v_exp_f32_e32 v251, v251
	v_add_f32_e32 v244, 1.0, v244
	v_add_f32_e32 v245, 1.0, v245
	v_add_f32_e32 v246, 1.0, v246
	v_add_f32_e32 v247, 1.0, v247
	v_add_f32_e32 v248, 1.0, v248
	v_add_f32_e32 v249, 1.0, v249
	v_add_f32_e32 v250, 1.0, v250
	v_add_f32_e32 v251, 1.0, v251
	v_pk_mul_f32 v[132:133], v[132:133], v[244:245]
	v_pk_mul_f32 v[134:135], v[134:135], v[246:247]
	v_pk_mul_f32 v[136:137], v[136:137], v[248:249]
	v_pk_mul_f32 v[138:139], v[138:139], v[250:251]
	v_pk_mul_f32 v[120:121], v[120:121], v[132:133]
	v_pk_mul_f32 v[122:123], v[122:123], v[134:135]
	v_pk_mul_f32 v[116:117], v[116:117], v[136:137]
	v_pk_mul_f32 v[118:119], v[118:119], v[138:139]
	s_waitcnt vmcnt(14)
;     static __device__ __forceinline__ float e1(float x) { return 1.0f + __expf(-fminf(fmaxf(x, -60.f), 60.f)); }
;     __device__ __forceinline__ void operator()(f32x4 (&acc)[2][2][4][2], const Unit& u, int wr, int wc, int fr, int fq) const {
;     ...
;                     const int col = col0 + bj * HALF;
;                     const bf16_t* gp = proj + (size_t)row * NP + C_GATE + u.z * D + col;
;                     const u32x4 ga = *(const u32x4*)gp;
;                     float sc[8];
;                     { float a[8]; unpack8(ga, a);
; #pragma unroll
;                       for (int j = 0; j < 8; ++j) sc[j] = __builtin_amdgcn_rcpf(e1(a[j])); }
;                     if (u.z < 2) { const u32x4 gb = *(const u32x4*)(gp + D); float b[8]; unpack8(gb, b);
; #pragma unroll
;                       for (int j = 0; j < 8; ++j) sc[j] *= e1(b[j]); }
;                     f32x4 v0 = acc[ai][bj][m][0], v1 = acc[ai][bj][m][1];
;                     v0[0] *= sc[0]; v0[1] *= sc[1]; v0[2] *= sc[2]; v0[3] *= sc[3]; v1[0] *= sc[4]; v1[1] *= sc[5]; v1[2] *= sc[6]; v1[3] *= sc[7];
;                     if (u.z < 2) { acc[ai][bj][m][0] = v0; acc[ai][bj][m][1] = v1; }
	v_lshlrev_b32_e32 v132, 16, v186
	v_and_b32_e32 v133, 0xffff0000, v186
	v_lshlrev_b32_e32 v134, 16, v187
	v_and_b32_e32 v135, 0xffff0000, v187
	v_lshlrev_b32_e32 v136, 16, v188
	v_and_b32_e32 v137, 0xffff0000, v188
	v_lshlrev_b32_e32 v138, 16, v189
	v_and_b32_e32 v139, 0xffff0000, v189
	v_lshlrev_b32_e32 v244, 16, v190
	v_and_b32_e32 v245, 0xffff0000, v190
	v_lshlrev_b32_e32 v246, 16, v191
	v_and_b32_e32 v247, 0xffff0000, v191
	v_lshlrev_b32_e32 v248, 16, v192
	v_and_b32_e32 v249, 0xffff0000, v192
	v_lshlrev_b32_e32 v250, 16, v193
	v_and_b32_e32 v251, 0xffff0000, v193
	s_mov_b64 s[8:9], 0x4c8000
	v_lshl_add_u64 v[156:157], v[152:153], 0, s[8:9]
	global_load_dwordx4 v[186:189], v[156:157], off offset:-3840
	global_load_dwordx4 v[190:193], v[156:157], off offset:256
	v_med3_f32 v132, v132, s97, v226
	v_med3_f32 v133, v133, s97, v226
	v_med3_f32 v134, v134, s97, v226
	v_med3_f32 v135, v135, s97, v226
	v_med3_f32 v136, v136, s97, v226
	v_med3_f32 v137, v137, s97, v226
	v_med3_f32 v138, v138, s97, v226
	v_med3_f32 v139, v139, s97, v226
	v_mul_f32_e32 v132, 0xbfb8aa3b, v132
	v_mul_f32_e32 v133, 0xbfb8aa3b, v133
	v_mul_f32_e32 v134, 0xbfb8aa3b, v134
	v_mul_f32_e32 v135, 0xbfb8aa3b, v135
	v_mul_f32_e32 v136, 0xbfb8aa3b, v136
	v_mul_f32_e32 v137, 0xbfb8aa3b, v137
	v_mul_f32_e32 v138, 0xbfb8aa3b, v138
	v_mul_f32_e32 v139, 0xbfb8aa3b, v139
	v_exp_f32_e32 v132, v132
	v_exp_f32_e32 v133, v133
	v_exp_f32_e32 v134, v134
	v_exp_f32_e32 v135, v135
	v_exp_f32_e32 v136, v136
	v_exp_f32_e32 v137, v137
	v_exp_f32_e32 v138, v138
	v_exp_f32_e32 v139, v139
	v_add_f32_e32 v132, 1.0, v132
	v_add_f32_e32 v133, 1.0, v133
	v_add_f32_e32 v134, 1.0, v134
	v_add_f32_e32 v135, 1.0, v135
	v_add_f32_e32 v136, 1.0, v136
	v_add_f32_e32 v137, 1.0, v137
	v_add_f32_e32 v138, 1.0, v138
	v_add_f32_e32 v139, 1.0, v139
	v_rcp_f32_e32 v132, v132
	v_rcp_f32_e32 v133, v133
	v_rcp_f32_e32 v134, v134
	v_rcp_f32_e32 v135, v135
	v_rcp_f32_e32 v136, v136
	v_rcp_f32_e32 v137, v137
	v_rcp_f32_e32 v138, v138
	v_rcp_f32_e32 v139, v139
	v_med3_f32 v244, v244, s97, v226
	v_med3_f32 v245, v245, s97, v226
	v_med3_f32 v246, v246, s97, v226
	v_med3_f32 v247, v247, s97, v226
	v_med3_f32 v248, v248, s97, v226
	v_med3_f32 v249, v249, s97, v226
	v_med3_f32 v250, v250, s97, v226
	v_med3_f32 v251, v251, s97, v226
	v_mul_f32_e32 v244, 0xbfb8aa3b, v244
	v_mul_f32_e32 v245, 0xbfb8aa3b, v245
	v_mul_f32_e32 v246, 0xbfb8aa3b, v246
	v_mul_f32_e32 v247, 0xbfb8aa3b, v247
	v_mul_f32_e32 v248, 0xbfb8aa3b, v248
	v_mul_f32_e32 v249, 0xbfb8aa3b, v249
	v_mul_f32_e32 v250, 0xbfb8aa3b, v250
	v_mul_f32_e32 v251, 0xbfb8aa3b, v251
	v_exp_f32_e32 v244, v244
	v_exp_f32_e32 v245, v245
	v_exp_f32_e32 v246, v246
	v_exp_f32_e32 v247, v247
	v_exp_f32_e32 v248, v248
	v_exp_f32_e32 v249, v249
	v_exp_f32_e32 v250, v250
	v_exp_f32_e32 v251, v251
	v_add_f32_e32 v244, 1.0, v244
	v_add_f32_e32 v245, 1.0, v245
	v_add_f32_e32 v246, 1.0, v246
	v_add_f32_e32 v247, 1.0, v247
	v_add_f32_e32 v248, 1.0, v248
	v_add_f32_e32 v249, 1.0, v249
	v_add_f32_e32 v250, 1.0, v250
	v_add_f32_e32 v251, 1.0, v251
	v_pk_mul_f32 v[132:133], v[132:133], v[244:245]
	v_pk_mul_f32 v[134:135], v[134:135], v[246:247]
	v_pk_mul_f32 v[136:137], v[136:137], v[248:249]
	v_pk_mul_f32 v[138:139], v[138:139], v[250:251]
	v_pk_mul_f32 v[88:89], v[88:89], v[132:133]
	v_pk_mul_f32 v[90:91], v[90:91], v[134:135]
	v_pk_mul_f32 v[84:85], v[84:85], v[136:137]
	v_pk_mul_f32 v[86:87], v[86:87], v[138:139]
	s_waitcnt vmcnt(14)
	v_lshlrev_b32_e32 v132, 16, v194
	v_and_b32_e32 v133, 0xffff0000, v194
	v_lshlrev_b32_e32 v134, 16, v195
	v_and_b32_e32 v135, 0xffff0000, v195
	v_lshlrev_b32_e32 v136, 16, v196
	v_and_b32_e32 v137, 0xffff0000, v196
	v_lshlrev_b32_e32 v138, 16, v197
	v_and_b32_e32 v139, 0xffff0000, v197
	v_lshlrev_b32_e32 v244, 16, v198
	v_and_b32_e32 v245, 0xffff0000, v198
	v_lshlrev_b32_e32 v246, 16, v199
	v_and_b32_e32 v247, 0xffff0000, v199
	v_lshlrev_b32_e32 v248, 16, v200
	v_and_b32_e32 v249, 0xffff0000, v200
	v_lshlrev_b32_e32 v250, 16, v201
	v_and_b32_e32 v251, 0xffff0000, v201
	s_mov_b64 s[8:9], 0x550000
	v_lshl_add_u64 v[156:157], v[152:153], 0, s[8:9]
	global_load_dwordx4 v[194:197], v[156:157], off offset:-4096
	global_load_dwordx4 v[198:201], v[156:157], off offset:0
	v_med3_f32 v132, v132, s97, v226
	v_med3_f32 v133, v133, s97, v226
	v_med3_f32 v134, v134, s97, v226
	v_med3_f32 v135, v135, s97, v226
	v_med3_f32 v136, v136, s97, v226
	v_med3_f32 v137, v137, s97, v226
	v_med3_f32 v138, v138, s97, v226
	v_med3_f32 v139, v139, s97, v226
	v_mul_f32_e32 v132, 0xbfb8aa3b, v132
	v_mul_f32_e32 v133, 0xbfb8aa3b, v133
	v_mul_f32_e32 v134, 0xbfb8aa3b, v134
	v_mul_f32_e32 v135, 0xbfb8aa3b, v135
	v_mul_f32_e32 v136, 0xbfb8aa3b, v136
	v_mul_f32_e32 v137, 0xbfb8aa3b, v137
	v_mul_f32_e32 v138, 0xbfb8aa3b, v138
	v_mul_f32_e32 v139, 0xbfb8aa3b, v139
	v_exp_f32_e32 v132, v132
	v_exp_f32_e32 v133, v133
	v_exp_f32_e32 v134, v134
	v_exp_f32_e32 v135, v135
	v_exp_f32_e32 v136, v136
	v_exp_f32_e32 v137, v137
	v_exp_f32_e32 v138, v138
	v_exp_f32_e32 v139, v139
	v_add_f32_e32 v132, 1.0, v132
	v_add_f32_e32 v133, 1.0, v133
	v_add_f32_e32 v134, 1.0, v134
	v_add_f32_e32 v135, 1.0, v135
	v_add_f32_e32 v136, 1.0, v136
	v_add_f32_e32 v137, 1.0, v137
	v_add_f32_e32 v138, 1.0, v138
	v_add_f32_e32 v139, 1.0, v139
	v_rcp_f32_e32 v132, v132
	v_rcp_f32_e32 v133, v133
	v_rcp_f32_e32 v134, v134
	v_rcp_f32_e32 v135, v135
	v_rcp_f32_e32 v136, v136
	v_rcp_f32_e32 v137, v137
	v_rcp_f32_e32 v138, v138
	v_rcp_f32_e32 v139, v139
	v_med3_f32 v244, v244, s97, v226
	v_med3_f32 v245, v245, s97, v226
	v_med3_f32 v246, v246, s97, v226
	v_med3_f32 v247, v247, s97, v226
	v_med3_f32 v248, v248, s97, v226
	v_med3_f32 v249, v249, s97, v226
	v_med3_f32 v250, v250, s97, v226
	v_med3_f32 v251, v251, s97, v226
	v_mul_f32_e32 v244, 0xbfb8aa3b, v244
	v_mul_f32_e32 v245, 0xbfb8aa3b, v245
	v_mul_f32_e32 v246, 0xbfb8aa3b, v246
	v_mul_f32_e32 v247, 0xbfb8aa3b, v247
	v_mul_f32_e32 v248, 0xbfb8aa3b, v248
	v_mul_f32_e32 v249, 0xbfb8aa3b, v249
	v_mul_f32_e32 v250, 0xbfb8aa3b, v250
	v_mul_f32_e32 v251, 0xbfb8aa3b, v251
	v_exp_f32_e32 v244, v244
	v_exp_f32_e32 v245, v245
	v_exp_f32_e32 v246, v246
	v_exp_f32_e32 v247, v247
	v_exp_f32_e32 v248, v248
	v_exp_f32_e32 v249, v249
	v_exp_f32_e32 v250, v250
	v_exp_f32_e32 v251, v251
	v_add_f32_e32 v244, 1.0, v244
	v_add_f32_e32 v245, 1.0, v245
	v_add_f32_e32 v246, 1.0, v246
	v_add_f32_e32 v247, 1.0, v247
	v_add_f32_e32 v248, 1.0, v248
	v_add_f32_e32 v249, 1.0, v249
	v_add_f32_e32 v250, 1.0, v250
	v_add_f32_e32 v251, 1.0, v251
	v_pk_mul_f32 v[132:133], v[132:133], v[244:245]
	v_pk_mul_f32 v[134:135], v[134:135], v[246:247]
	v_pk_mul_f32 v[136:137], v[136:137], v[248:249]
	v_pk_mul_f32 v[138:139], v[138:139], v[250:251]
	v_pk_mul_f32 v[112:113], v[112:113], v[132:133]
	v_pk_mul_f32 v[114:115], v[114:115], v[134:135]
	v_pk_mul_f32 v[108:109], v[108:109], v[136:137]
	v_pk_mul_f32 v[110:111], v[110:111], v[138:139]
	s_waitcnt vmcnt(14)
;     static __device__ __forceinline__ float e1(float x) { return 1.0f + __expf(-fminf(fmaxf(x, -60.f), 60.f)); }
;     __device__ __forceinline__ void operator()(f32x4 (&acc)[2][2][4][2], const Unit& u, int wr, int wc, int fr, int fq) const {
;     ...
;                     const int col = col0 + bj * HALF;
;                     const bf16_t* gp = proj + (size_t)row * NP + C_GATE + u.z * D + col;
;                     const u32x4 ga = *(const u32x4*)gp;
;                     float sc[8];
;                     { float a[8]; unpack8(ga, a);
; #pragma unroll
;                       for (int j = 0; j < 8; ++j) sc[j] = __builtin_amdgcn_rcpf(e1(a[j])); }
;                     if (u.z < 2) { const u32x4 gb = *(const u32x4*)(gp + D); float b[8]; unpack8(gb, b);
; #pragma unroll
;                       for (int j = 0; j < 8; ++j) sc[j] *= e1(b[j]); }
;                     f32x4 v0 = acc[ai][bj][m][0], v1 = acc[ai][bj][m][1];
;                     v0[0] *= sc[0]; v0[1] *= sc[1]; v0[2] *= sc[2]; v0[3] *= sc[3]; v1[0] *= sc[4]; v1[1] *= sc[5]; v1[2] *= sc[6]; v1[3] *= sc[7];
;                     if (u.z < 2) { acc[ai][bj][m][0] = v0; acc[ai][bj][m][1] = v1; }
	v_lshlrev_b32_e32 v132, 16, v206
	v_and_b32_e32 v133, 0xffff0000, v206
	v_lshlrev_b32_e32 v134, 16, v207
	v_and_b32_e32 v135, 0xffff0000, v207
	v_lshlrev_b32_e32 v136, 16, v208
	v_and_b32_e32 v137, 0xffff0000, v208
	v_lshlrev_b32_e32 v138, 16, v209
	v_and_b32_e32 v139, 0xffff0000, v209
	v_lshlrev_b32_e32 v244, 16, v210
	v_and_b32_e32 v245, 0xffff0000, v210
	v_lshlrev_b32_e32 v246, 16, v211
	v_and_b32_e32 v247, 0xffff0000, v211
	v_lshlrev_b32_e32 v248, 16, v212
	v_and_b32_e32 v249, 0xffff0000, v212
	v_lshlrev_b32_e32 v250, 16, v213
	v_and_b32_e32 v251, 0xffff0000, v213
	s_mov_b64 s[8:9], 0x550000
	v_lshl_add_u64 v[156:157], v[152:153], 0, s[8:9]
	global_load_dwordx4 v[206:209], v[156:157], off offset:-3840
	global_load_dwordx4 v[210:213], v[156:157], off offset:256
	v_med3_f32 v132, v132, s97, v226
	v_med3_f32 v133, v133, s97, v226
	v_med3_f32 v134, v134, s97, v226
	v_med3_f32 v135, v135, s97, v226
	v_med3_f32 v136, v136, s97, v226
	v_med3_f32 v137, v137, s97, v226
	v_med3_f32 v138, v138, s97, v226
	v_med3_f32 v139, v139, s97, v226
	v_mul_f32_e32 v132, 0xbfb8aa3b, v132
	v_mul_f32_e32 v133, 0xbfb8aa3b, v133
	v_mul_f32_e32 v134, 0xbfb8aa3b, v134
	v_mul_f32_e32 v135, 0xbfb8aa3b, v135
	v_mul_f32_e32 v136, 0xbfb8aa3b, v136
	v_mul_f32_e32 v137, 0xbfb8aa3b, v137
	v_mul_f32_e32 v138, 0xbfb8aa3b, v138
	v_mul_f32_e32 v139, 0xbfb8aa3b, v139
	v_exp_f32_e32 v132, v132
	v_exp_f32_e32 v133, v133
	v_exp_f32_e32 v134, v134
	v_exp_f32_e32 v135, v135
	v_exp_f32_e32 v136, v136
	v_exp_f32_e32 v137, v137
	v_exp_f32_e32 v138, v138
	v_exp_f32_e32 v139, v139
	v_add_f32_e32 v132, 1.0, v132
	v_add_f32_e32 v133, 1.0, v133
	v_add_f32_e32 v134, 1.0, v134
	v_add_f32_e32 v135, 1.0, v135
	v_add_f32_e32 v136, 1.0, v136
	v_add_f32_e32 v137, 1.0, v137
	v_add_f32_e32 v138, 1.0, v138
	v_add_f32_e32 v139, 1.0, v139
	v_rcp_f32_e32 v132, v132
	v_rcp_f32_e32 v133, v133
	v_rcp_f32_e32 v134, v134
	v_rcp_f32_e32 v135, v135
	v_rcp_f32_e32 v136, v136
	v_rcp_f32_e32 v137, v137
	v_rcp_f32_e32 v138, v138
	v_rcp_f32_e32 v139, v139
	v_med3_f32 v244, v244, s97, v226
	v_med3_f32 v245, v245, s97, v226
	v_med3_f32 v246, v246, s97, v226
	v_med3_f32 v247, v247, s97, v226
	v_med3_f32 v248, v248, s97, v226
	v_med3_f32 v249, v249, s97, v226
	v_med3_f32 v250, v250, s97, v226
	v_med3_f32 v251, v251, s97, v226
	v_mul_f32_e32 v244, 0xbfb8aa3b, v244
	v_mul_f32_e32 v245, 0xbfb8aa3b, v245
	v_mul_f32_e32 v246, 0xbfb8aa3b, v246
	v_mul_f32_e32 v247, 0xbfb8aa3b, v247
	v_mul_f32_e32 v248, 0xbfb8aa3b, v248
	v_mul_f32_e32 v249, 0xbfb8aa3b, v249
	v_mul_f32_e32 v250, 0xbfb8aa3b, v250
	v_mul_f32_e32 v251, 0xbfb8aa3b, v251
	v_exp_f32_e32 v244, v244
	v_exp_f32_e32 v245, v245
	v_exp_f32_e32 v246, v246
	v_exp_f32_e32 v247, v247
	v_exp_f32_e32 v248, v248
	v_exp_f32_e32 v249, v249
	v_exp_f32_e32 v250, v250
	v_exp_f32_e32 v251, v251
	v_add_f32_e32 v244, 1.0, v244
	v_add_f32_e32 v245, 1.0, v245
	v_add_f32_e32 v246, 1.0, v246
	v_add_f32_e32 v247, 1.0, v247
	v_add_f32_e32 v248, 1.0, v248
	v_add_f32_e32 v249, 1.0, v249
	v_add_f32_e32 v250, 1.0, v250
	v_add_f32_e32 v251, 1.0, v251
	v_pk_mul_f32 v[132:133], v[132:133], v[244:245]
	v_pk_mul_f32 v[134:135], v[134:135], v[246:247]
	v_pk_mul_f32 v[136:137], v[136:137], v[248:249]
	v_pk_mul_f32 v[138:139], v[138:139], v[250:251]
	v_pk_mul_f32 v[80:81], v[80:81], v[132:133]
	v_pk_mul_f32 v[82:83], v[82:83], v[134:135]
	v_pk_mul_f32 v[76:77], v[76:77], v[136:137]
	v_pk_mul_f32 v[78:79], v[78:79], v[138:139]
	s_waitcnt vmcnt(14)
	v_lshlrev_b32_e32 v132, 16, v228
	v_and_b32_e32 v133, 0xffff0000, v228
	v_lshlrev_b32_e32 v134, 16, v229
	v_and_b32_e32 v135, 0xffff0000, v229
	v_lshlrev_b32_e32 v136, 16, v230
	v_and_b32_e32 v137, 0xffff0000, v230
	v_lshlrev_b32_e32 v138, 16, v231
	v_and_b32_e32 v139, 0xffff0000, v231
	v_lshlrev_b32_e32 v244, 16, v232
	v_and_b32_e32 v245, 0xffff0000, v232
	v_lshlrev_b32_e32 v246, 16, v233
	v_and_b32_e32 v247, 0xffff0000, v233
	v_lshlrev_b32_e32 v248, 16, v234
	v_and_b32_e32 v249, 0xffff0000, v234
	v_lshlrev_b32_e32 v250, 16, v235
	v_and_b32_e32 v251, 0xffff0000, v235
	s_mov_b64 s[8:9], 0x5d8000
	v_lshl_add_u64 v[156:157], v[152:153], 0, s[8:9]
	global_load_dwordx4 v[228:231], v[156:157], off offset:-4096
	global_load_dwordx4 v[232:235], v[156:157], off offset:0
	v_med3_f32 v132, v132, s97, v226
	v_med3_f32 v133, v133, s97, v226
	v_med3_f32 v134, v134, s97, v226
	v_med3_f32 v135, v135, s97, v226
	v_med3_f32 v136, v136, s97, v226
	v_med3_f32 v137, v137, s97, v226
	v_med3_f32 v138, v138, s97, v226
	v_med3_f32 v139, v139, s97, v226
	v_mul_f32_e32 v132, 0xbfb8aa3b, v132
	v_mul_f32_e32 v133, 0xbfb8aa3b, v133
	v_mul_f32_e32 v134, 0xbfb8aa3b, v134
	v_mul_f32_e32 v135, 0xbfb8aa3b, v135
	v_mul_f32_e32 v136, 0xbfb8aa3b, v136
	v_mul_f32_e32 v137, 0xbfb8aa3b, v137
	v_mul_f32_e32 v138, 0xbfb8aa3b, v138
	v_mul_f32_e32 v139, 0xbfb8aa3b, v139
	v_exp_f32_e32 v132, v132
	v_exp_f32_e32 v133, v133
	v_exp_f32_e32 v134, v134
	v_exp_f32_e32 v135, v135
	v_exp_f32_e32 v136, v136
	v_exp_f32_e32 v137, v137
	v_exp_f32_e32 v138, v138
	v_exp_f32_e32 v139, v139
	v_add_f32_e32 v132, 1.0, v132
	v_add_f32_e32 v133, 1.0, v133
	v_add_f32_e32 v134, 1.0, v134
	v_add_f32_e32 v135, 1.0, v135
	v_add_f32_e32 v136, 1.0, v136
	v_add_f32_e32 v137, 1.0, v137
	v_add_f32_e32 v138, 1.0, v138
	v_add_f32_e32 v139, 1.0, v139
	v_rcp_f32_e32 v132, v132
	v_rcp_f32_e32 v133, v133
	v_rcp_f32_e32 v134, v134
	v_rcp_f32_e32 v135, v135
	v_rcp_f32_e32 v136, v136
	v_rcp_f32_e32 v137, v137
	v_rcp_f32_e32 v138, v138
	v_rcp_f32_e32 v139, v139
	v_med3_f32 v244, v244, s97, v226
	v_med3_f32 v245, v245, s97, v226
	v_med3_f32 v246, v246, s97, v226
	v_med3_f32 v247, v247, s97, v226
	v_med3_f32 v248, v248, s97, v226
	v_med3_f32 v249, v249, s97, v226
	v_med3_f32 v250, v250, s97, v226
	v_med3_f32 v251, v251, s97, v226
	v_mul_f32_e32 v244, 0xbfb8aa3b, v244
	v_mul_f32_e32 v245, 0xbfb8aa3b, v245
	v_mul_f32_e32 v246, 0xbfb8aa3b, v246
	v_mul_f32_e32 v247, 0xbfb8aa3b, v247
	v_mul_f32_e32 v248, 0xbfb8aa3b, v248
	v_mul_f32_e32 v249, 0xbfb8aa3b, v249
	v_mul_f32_e32 v250, 0xbfb8aa3b, v250
	v_mul_f32_e32 v251, 0xbfb8aa3b, v251
	v_exp_f32_e32 v244, v244
	v_exp_f32_e32 v245, v245
	v_exp_f32_e32 v246, v246
	v_exp_f32_e32 v247, v247
	v_exp_f32_e32 v248, v248
	v_exp_f32_e32 v249, v249
	v_exp_f32_e32 v250, v250
	v_exp_f32_e32 v251, v251
	v_add_f32_e32 v244, 1.0, v244
	v_add_f32_e32 v245, 1.0, v245
	v_add_f32_e32 v246, 1.0, v246
	v_add_f32_e32 v247, 1.0, v247
	v_add_f32_e32 v248, 1.0, v248
	v_add_f32_e32 v249, 1.0, v249
	v_add_f32_e32 v250, 1.0, v250
	v_add_f32_e32 v251, 1.0, v251
	v_pk_mul_f32 v[132:133], v[132:133], v[244:245]
	v_pk_mul_f32 v[134:135], v[134:135], v[246:247]
	v_pk_mul_f32 v[136:137], v[136:137], v[248:249]
	v_pk_mul_f32 v[138:139], v[138:139], v[250:251]
	v_pk_mul_f32 v[104:105], v[104:105], v[132:133]
	v_pk_mul_f32 v[106:107], v[106:107], v[134:135]
	v_pk_mul_f32 v[100:101], v[100:101], v[136:137]
	v_pk_mul_f32 v[102:103], v[102:103], v[138:139]
	s_waitcnt vmcnt(14)
;     static __device__ __forceinline__ float e1(float x) { return 1.0f + __expf(-fminf(fmaxf(x, -60.f), 60.f)); }
;     __device__ __forceinline__ void operator()(f32x4 (&acc)[2][2][4][2], const Unit& u, int wr, int wc, int fr, int fq) const {
;     ...
;                     const int col = col0 + bj * HALF;
;                     const bf16_t* gp = proj + (size_t)row * NP + C_GATE + u.z * D + col;
;                     const u32x4 ga = *(const u32x4*)gp;
;                     float sc[8];
;                     { float a[8]; unpack8(ga, a);
; #pragma unroll
;                       for (int j = 0; j < 8; ++j) sc[j] = __builtin_amdgcn_rcpf(e1(a[j])); }
;                     if (u.z < 2) { const u32x4 gb = *(const u32x4*)(gp + D); float b[8]; unpack8(gb, b);
; #pragma unroll
;                       for (int j = 0; j < 8; ++j) sc[j] *= e1(b[j]); }
;                     f32x4 v0 = acc[ai][bj][m][0], v1 = acc[ai][bj][m][1];
;                     v0[0] *= sc[0]; v0[1] *= sc[1]; v0[2] *= sc[2]; v0[3] *= sc[3]; v1[0] *= sc[4]; v1[1] *= sc[5]; v1[2] *= sc[6]; v1[3] *= sc[7];
;                     if (u.z < 2) { acc[ai][bj][m][0] = v0; acc[ai][bj][m][1] = v1; }
	v_lshlrev_b32_e32 v132, 16, v236
	v_and_b32_e32 v133, 0xffff0000, v236
	v_lshlrev_b32_e32 v134, 16, v237
	v_and_b32_e32 v135, 0xffff0000, v237
	v_lshlrev_b32_e32 v136, 16, v238
	v_and_b32_e32 v137, 0xffff0000, v238
	v_lshlrev_b32_e32 v138, 16, v239
	v_and_b32_e32 v139, 0xffff0000, v239
	v_lshlrev_b32_e32 v244, 16, v240
	v_and_b32_e32 v245, 0xffff0000, v240
	v_lshlrev_b32_e32 v246, 16, v241
	v_and_b32_e32 v247, 0xffff0000, v241
	v_lshlrev_b32_e32 v248, 16, v242
	v_and_b32_e32 v249, 0xffff0000, v242
	v_lshlrev_b32_e32 v250, 16, v243
	v_and_b32_e32 v251, 0xffff0000, v243
	s_mov_b64 s[8:9], 0x5d8000
	v_lshl_add_u64 v[156:157], v[152:153], 0, s[8:9]
	global_load_dwordx4 v[236:239], v[156:157], off offset:-3840
	global_load_dwordx4 v[240:243], v[156:157], off offset:256
	v_med3_f32 v132, v132, s97, v226
	v_med3_f32 v133, v133, s97, v226
	v_med3_f32 v134, v134, s97, v226
	v_med3_f32 v135, v135, s97, v226
	v_med3_f32 v136, v136, s97, v226
	v_med3_f32 v137, v137, s97, v226
	v_med3_f32 v138, v138, s97, v226
	v_med3_f32 v139, v139, s97, v226
	v_mul_f32_e32 v132, 0xbfb8aa3b, v132
	v_mul_f32_e32 v133, 0xbfb8aa3b, v133
	v_mul_f32_e32 v134, 0xbfb8aa3b, v134
	v_mul_f32_e32 v135, 0xbfb8aa3b, v135
	v_mul_f32_e32 v136, 0xbfb8aa3b, v136
	v_mul_f32_e32 v137, 0xbfb8aa3b, v137
	v_mul_f32_e32 v138, 0xbfb8aa3b, v138
	v_mul_f32_e32 v139, 0xbfb8aa3b, v139
	v_exp_f32_e32 v132, v132
	v_exp_f32_e32 v133, v133
	v_exp_f32_e32 v134, v134
	v_exp_f32_e32 v135, v135
	v_exp_f32_e32 v136, v136
	v_exp_f32_e32 v137, v137
	v_exp_f32_e32 v138, v138
	v_exp_f32_e32 v139, v139
	v_add_f32_e32 v132, 1.0, v132
	v_add_f32_e32 v133, 1.0, v133
	v_add_f32_e32 v134, 1.0, v134
	v_add_f32_e32 v135, 1.0, v135
	v_add_f32_e32 v136, 1.0, v136
	v_add_f32_e32 v137, 1.0, v137
	v_add_f32_e32 v138, 1.0, v138
	v_add_f32_e32 v139, 1.0, v139
	v_rcp_f32_e32 v132, v132
	v_rcp_f32_e32 v133, v133
	v_rcp_f32_e32 v134, v134
	v_rcp_f32_e32 v135, v135
	v_rcp_f32_e32 v136, v136
	v_rcp_f32_e32 v137, v137
	v_rcp_f32_e32 v138, v138
	v_rcp_f32_e32 v139, v139
	v_med3_f32 v244, v244, s97, v226
	v_med3_f32 v245, v245, s97, v226
	v_med3_f32 v246, v246, s97, v226
	v_med3_f32 v247, v247, s97, v226
	v_med3_f32 v248, v248, s97, v226
	v_med3_f32 v249, v249, s97, v226
	v_med3_f32 v250, v250, s97, v226
	v_med3_f32 v251, v251, s97, v226
	v_mul_f32_e32 v244, 0xbfb8aa3b, v244
	v_mul_f32_e32 v245, 0xbfb8aa3b, v245
	v_mul_f32_e32 v246, 0xbfb8aa3b, v246
	v_mul_f32_e32 v247, 0xbfb8aa3b, v247
	v_mul_f32_e32 v248, 0xbfb8aa3b, v248
	v_mul_f32_e32 v249, 0xbfb8aa3b, v249
	v_mul_f32_e32 v250, 0xbfb8aa3b, v250
	v_mul_f32_e32 v251, 0xbfb8aa3b, v251
	v_exp_f32_e32 v244, v244
	v_exp_f32_e32 v245, v245
	v_exp_f32_e32 v246, v246
	v_exp_f32_e32 v247, v247
	v_exp_f32_e32 v248, v248
	v_exp_f32_e32 v249, v249
	v_exp_f32_e32 v250, v250
	v_exp_f32_e32 v251, v251
	v_add_f32_e32 v244, 1.0, v244
	v_add_f32_e32 v245, 1.0, v245
	v_add_f32_e32 v246, 1.0, v246
	v_add_f32_e32 v247, 1.0, v247
	v_add_f32_e32 v248, 1.0, v248
	v_add_f32_e32 v249, 1.0, v249
	v_add_f32_e32 v250, 1.0, v250
	v_add_f32_e32 v251, 1.0, v251
	v_pk_mul_f32 v[132:133], v[132:133], v[244:245]
	v_pk_mul_f32 v[134:135], v[134:135], v[246:247]
	v_pk_mul_f32 v[136:137], v[136:137], v[248:249]
	v_pk_mul_f32 v[138:139], v[138:139], v[250:251]
	v_pk_mul_f32 v[72:73], v[72:73], v[132:133]
	v_pk_mul_f32 v[74:75], v[74:75], v[134:135]
	v_pk_mul_f32 v[68:69], v[68:69], v[136:137]
	v_pk_mul_f32 v[70:71], v[70:71], v[138:139]
	s_waitcnt vmcnt(14)
	v_lshlrev_b32_e32 v132, 16, v162
	v_and_b32_e32 v133, 0xffff0000, v162
	v_lshlrev_b32_e32 v134, 16, v163
	v_and_b32_e32 v135, 0xffff0000, v163
	v_lshlrev_b32_e32 v136, 16, v164
	v_and_b32_e32 v137, 0xffff0000, v164
	v_lshlrev_b32_e32 v138, 16, v165
	v_and_b32_e32 v139, 0xffff0000, v165
	v_lshlrev_b32_e32 v244, 16, v166
	v_and_b32_e32 v245, 0xffff0000, v166
	v_lshlrev_b32_e32 v246, 16, v167
	v_and_b32_e32 v247, 0xffff0000, v167
	v_lshlrev_b32_e32 v248, 16, v168
	v_and_b32_e32 v249, 0xffff0000, v168
	v_lshlrev_b32_e32 v250, 16, v169
	v_and_b32_e32 v251, 0xffff0000, v169
	v_med3_f32 v132, v132, s97, v226
	v_med3_f32 v133, v133, s97, v226
	v_med3_f32 v134, v134, s97, v226
	v_med3_f32 v135, v135, s97, v226
	v_med3_f32 v136, v136, s97, v226
	v_med3_f32 v137, v137, s97, v226
	v_med3_f32 v138, v138, s97, v226
	v_med3_f32 v139, v139, s97, v226
	v_mul_f32_e32 v132, 0xbfb8aa3b, v132
	v_mul_f32_e32 v133, 0xbfb8aa3b, v133
	v_mul_f32_e32 v134, 0xbfb8aa3b, v134
	v_mul_f32_e32 v135, 0xbfb8aa3b, v135
	v_mul_f32_e32 v136, 0xbfb8aa3b, v136
	v_mul_f32_e32 v137, 0xbfb8aa3b, v137
	v_mul_f32_e32 v138, 0xbfb8aa3b, v138
	v_mul_f32_e32 v139, 0xbfb8aa3b, v139
	v_exp_f32_e32 v132, v132
	v_exp_f32_e32 v133, v133
	v_exp_f32_e32 v134, v134
	v_exp_f32_e32 v135, v135
	v_exp_f32_e32 v136, v136
	v_exp_f32_e32 v137, v137
	v_exp_f32_e32 v138, v138
	v_exp_f32_e32 v139, v139
	v_add_f32_e32 v132, 1.0, v132
	v_add_f32_e32 v133, 1.0, v133
	v_add_f32_e32 v134, 1.0, v134
	v_add_f32_e32 v135, 1.0, v135
	v_add_f32_e32 v136, 1.0, v136
	v_add_f32_e32 v137, 1.0, v137
	v_add_f32_e32 v138, 1.0, v138
	v_add_f32_e32 v139, 1.0, v139
	v_rcp_f32_e32 v132, v132
	v_rcp_f32_e32 v133, v133
	v_rcp_f32_e32 v134, v134
	v_rcp_f32_e32 v135, v135
	v_rcp_f32_e32 v136, v136
	v_rcp_f32_e32 v137, v137
	v_rcp_f32_e32 v138, v138
	v_rcp_f32_e32 v139, v139
	v_med3_f32 v244, v244, s97, v226
	v_med3_f32 v245, v245, s97, v226
	v_med3_f32 v246, v246, s97, v226
	v_med3_f32 v247, v247, s97, v226
	v_med3_f32 v248, v248, s97, v226
	v_med3_f32 v249, v249, s97, v226
	v_med3_f32 v250, v250, s97, v226
	v_med3_f32 v251, v251, s97, v226
	v_mul_f32_e32 v244, 0xbfb8aa3b, v244
	v_mul_f32_e32 v245, 0xbfb8aa3b, v245
	v_mul_f32_e32 v246, 0xbfb8aa3b, v246
	v_mul_f32_e32 v247, 0xbfb8aa3b, v247
	v_mul_f32_e32 v248, 0xbfb8aa3b, v248
	v_mul_f32_e32 v249, 0xbfb8aa3b, v249
	v_mul_f32_e32 v250, 0xbfb8aa3b, v250
	v_mul_f32_e32 v251, 0xbfb8aa3b, v251
	v_exp_f32_e32 v244, v244
	v_exp_f32_e32 v245, v245
	v_exp_f32_e32 v246, v246
	v_exp_f32_e32 v247, v247
	v_exp_f32_e32 v248, v248
	v_exp_f32_e32 v249, v249
	v_exp_f32_e32 v250, v250
	v_exp_f32_e32 v251, v251
	v_add_f32_e32 v244, 1.0, v244
	v_add_f32_e32 v245, 1.0, v245
	v_add_f32_e32 v246, 1.0, v246
	v_add_f32_e32 v247, 1.0, v247
	v_add_f32_e32 v248, 1.0, v248
	v_add_f32_e32 v249, 1.0, v249
	v_add_f32_e32 v250, 1.0, v250
	v_add_f32_e32 v251, 1.0, v251
	v_pk_mul_f32 v[132:133], v[132:133], v[244:245]
	v_pk_mul_f32 v[134:135], v[134:135], v[246:247]
	v_pk_mul_f32 v[136:137], v[136:137], v[248:249]
	v_pk_mul_f32 v[138:139], v[138:139], v[250:251]
	v_pk_mul_f32 v[64:65], v[64:65], v[132:133]
	v_pk_mul_f32 v[66:67], v[66:67], v[134:135]
	v_pk_mul_f32 v[60:61], v[60:61], v[136:137]
	v_pk_mul_f32 v[62:63], v[62:63], v[138:139]
	s_waitcnt vmcnt(12)
;     static __device__ __forceinline__ float e1(float x) { return 1.0f + __expf(-fminf(fmaxf(x, -60.f), 60.f)); }
;     __device__ __forceinline__ void operator()(f32x4 (&acc)[2][2][4][2], const Unit& u, int wr, int wc, int fr, int fq) const {
;     ...
;                     const int col = col0 + bj * HALF;
;                     const bf16_t* gp = proj + (size_t)row * NP + C_GATE + u.z * D + col;
;                     const u32x4 ga = *(const u32x4*)gp;
;                     float sc[8];
;                     { float a[8]; unpack8(ga, a);
; #pragma unroll
;                       for (int j = 0; j < 8; ++j) sc[j] = __builtin_amdgcn_rcpf(e1(a[j])); }
;                     if (u.z < 2) { const u32x4 gb = *(const u32x4*)(gp + D); float b[8]; unpack8(gb, b);
; #pragma unroll
;                       for (int j = 0; j < 8; ++j) sc[j] *= e1(b[j]); }
;                     f32x4 v0 = acc[ai][bj][m][0], v1 = acc[ai][bj][m][1];
;                     v0[0] *= sc[0]; v0[1] *= sc[1]; v0[2] *= sc[2]; v0[3] *= sc[3]; v1[0] *= sc[4]; v1[1] *= sc[5]; v1[2] *= sc[6]; v1[3] *= sc[7];
;                     if (u.z < 2) { acc[ai][bj][m][0] = v0; acc[ai][bj][m][1] = v1; }
	v_lshlrev_b32_e32 v132, 16, v170
	v_and_b32_e32 v133, 0xffff0000, v170
	v_lshlrev_b32_e32 v134, 16, v171
	v_and_b32_e32 v135, 0xffff0000, v171
	v_lshlrev_b32_e32 v136, 16, v172
	v_and_b32_e32 v137, 0xffff0000, v172
	v_lshlrev_b32_e32 v138, 16, v173
	v_and_b32_e32 v139, 0xffff0000, v173
	v_lshlrev_b32_e32 v244, 16, v174
	v_and_b32_e32 v245, 0xffff0000, v174
	v_lshlrev_b32_e32 v246, 16, v175
	v_and_b32_e32 v247, 0xffff0000, v175
	v_lshlrev_b32_e32 v248, 16, v176
	v_and_b32_e32 v249, 0xffff0000, v176
	v_lshlrev_b32_e32 v250, 16, v177
	v_and_b32_e32 v251, 0xffff0000, v177
	v_med3_f32 v132, v132, s97, v226
	v_med3_f32 v133, v133, s97, v226
	v_med3_f32 v134, v134, s97, v226
	v_med3_f32 v135, v135, s97, v226
	v_med3_f32 v136, v136, s97, v226
	v_med3_f32 v137, v137, s97, v226
	v_med3_f32 v138, v138, s97, v226
	v_med3_f32 v139, v139, s97, v226
	v_mul_f32_e32 v132, 0xbfb8aa3b, v132
	v_mul_f32_e32 v133, 0xbfb8aa3b, v133
	v_mul_f32_e32 v134, 0xbfb8aa3b, v134
	v_mul_f32_e32 v135, 0xbfb8aa3b, v135
	v_mul_f32_e32 v136, 0xbfb8aa3b, v136
	v_mul_f32_e32 v137, 0xbfb8aa3b, v137
	v_mul_f32_e32 v138, 0xbfb8aa3b, v138
	v_mul_f32_e32 v139, 0xbfb8aa3b, v139
	v_exp_f32_e32 v132, v132
	v_exp_f32_e32 v133, v133
	v_exp_f32_e32 v134, v134
	v_exp_f32_e32 v135, v135
	v_exp_f32_e32 v136, v136
	v_exp_f32_e32 v137, v137
	v_exp_f32_e32 v138, v138
	v_exp_f32_e32 v139, v139
	v_add_f32_e32 v132, 1.0, v132
	v_add_f32_e32 v133, 1.0, v133
	v_add_f32_e32 v134, 1.0, v134
	v_add_f32_e32 v135, 1.0, v135
	v_add_f32_e32 v136, 1.0, v136
	v_add_f32_e32 v137, 1.0, v137
	v_add_f32_e32 v138, 1.0, v138
	v_add_f32_e32 v139, 1.0, v139
	v_rcp_f32_e32 v132, v132
	v_rcp_f32_e32 v133, v133
	v_rcp_f32_e32 v134, v134
	v_rcp_f32_e32 v135, v135
	v_rcp_f32_e32 v136, v136
	v_rcp_f32_e32 v137, v137
	v_rcp_f32_e32 v138, v138
	v_rcp_f32_e32 v139, v139
	v_med3_f32 v244, v244, s97, v226
	v_med3_f32 v245, v245, s97, v226
	v_med3_f32 v246, v246, s97, v226
	v_med3_f32 v247, v247, s97, v226
	v_med3_f32 v248, v248, s97, v226
	v_med3_f32 v249, v249, s97, v226
	v_med3_f32 v250, v250, s97, v226
	v_med3_f32 v251, v251, s97, v226
	v_mul_f32_e32 v244, 0xbfb8aa3b, v244
	v_mul_f32_e32 v245, 0xbfb8aa3b, v245
	v_mul_f32_e32 v246, 0xbfb8aa3b, v246
	v_mul_f32_e32 v247, 0xbfb8aa3b, v247
	v_mul_f32_e32 v248, 0xbfb8aa3b, v248
	v_mul_f32_e32 v249, 0xbfb8aa3b, v249
	v_mul_f32_e32 v250, 0xbfb8aa3b, v250
	v_mul_f32_e32 v251, 0xbfb8aa3b, v251
	v_exp_f32_e32 v244, v244
	v_exp_f32_e32 v245, v245
	v_exp_f32_e32 v246, v246
	v_exp_f32_e32 v247, v247
	v_exp_f32_e32 v248, v248
	v_exp_f32_e32 v249, v249
	v_exp_f32_e32 v250, v250
	v_exp_f32_e32 v251, v251
	v_add_f32_e32 v244, 1.0, v244
	v_add_f32_e32 v245, 1.0, v245
	v_add_f32_e32 v246, 1.0, v246
	v_add_f32_e32 v247, 1.0, v247
	v_add_f32_e32 v248, 1.0, v248
	v_add_f32_e32 v249, 1.0, v249
	v_add_f32_e32 v250, 1.0, v250
	v_add_f32_e32 v251, 1.0, v251
	v_pk_mul_f32 v[132:133], v[132:133], v[244:245]
	v_pk_mul_f32 v[134:135], v[134:135], v[246:247]
	v_pk_mul_f32 v[136:137], v[136:137], v[248:249]
	v_pk_mul_f32 v[138:139], v[138:139], v[250:251]
	v_pk_mul_f32 v[32:33], v[32:33], v[132:133]
	v_pk_mul_f32 v[34:35], v[34:35], v[134:135]
	v_pk_mul_f32 v[28:29], v[28:29], v[136:137]
	v_pk_mul_f32 v[30:31], v[30:31], v[138:139]
	s_waitcnt vmcnt(10)
	v_lshlrev_b32_e32 v132, 16, v178
	v_and_b32_e32 v133, 0xffff0000, v178
	v_lshlrev_b32_e32 v134, 16, v179
	v_and_b32_e32 v135, 0xffff0000, v179
	v_lshlrev_b32_e32 v136, 16, v180
	v_and_b32_e32 v137, 0xffff0000, v180
	v_lshlrev_b32_e32 v138, 16, v181
	v_and_b32_e32 v139, 0xffff0000, v181
	v_lshlrev_b32_e32 v244, 16, v182
	v_and_b32_e32 v245, 0xffff0000, v182
	v_lshlrev_b32_e32 v246, 16, v183
	v_and_b32_e32 v247, 0xffff0000, v183
	v_lshlrev_b32_e32 v248, 16, v184
	v_and_b32_e32 v249, 0xffff0000, v184
	v_lshlrev_b32_e32 v250, 16, v185
	v_and_b32_e32 v251, 0xffff0000, v185
	v_med3_f32 v132, v132, s97, v226
	v_med3_f32 v133, v133, s97, v226
	v_med3_f32 v134, v134, s97, v226
	v_med3_f32 v135, v135, s97, v226
	v_med3_f32 v136, v136, s97, v226
	v_med3_f32 v137, v137, s97, v226
	v_med3_f32 v138, v138, s97, v226
	v_med3_f32 v139, v139, s97, v226
	v_mul_f32_e32 v132, 0xbfb8aa3b, v132
	v_mul_f32_e32 v133, 0xbfb8aa3b, v133
	v_mul_f32_e32 v134, 0xbfb8aa3b, v134
	v_mul_f32_e32 v135, 0xbfb8aa3b, v135
	v_mul_f32_e32 v136, 0xbfb8aa3b, v136
	v_mul_f32_e32 v137, 0xbfb8aa3b, v137
	v_mul_f32_e32 v138, 0xbfb8aa3b, v138
	v_mul_f32_e32 v139, 0xbfb8aa3b, v139
	v_exp_f32_e32 v132, v132
	v_exp_f32_e32 v133, v133
	v_exp_f32_e32 v134, v134
	v_exp_f32_e32 v135, v135
	v_exp_f32_e32 v136, v136
	v_exp_f32_e32 v137, v137
	v_exp_f32_e32 v138, v138
	v_exp_f32_e32 v139, v139
	v_add_f32_e32 v132, 1.0, v132
	v_add_f32_e32 v133, 1.0, v133
	v_add_f32_e32 v134, 1.0, v134
	v_add_f32_e32 v135, 1.0, v135
	v_add_f32_e32 v136, 1.0, v136
	v_add_f32_e32 v137, 1.0, v137
	v_add_f32_e32 v138, 1.0, v138
	v_add_f32_e32 v139, 1.0, v139
	v_rcp_f32_e32 v132, v132
	v_rcp_f32_e32 v133, v133
	v_rcp_f32_e32 v134, v134
	v_rcp_f32_e32 v135, v135
	v_rcp_f32_e32 v136, v136
	v_rcp_f32_e32 v137, v137
	v_rcp_f32_e32 v138, v138
	v_rcp_f32_e32 v139, v139
	v_med3_f32 v244, v244, s97, v226
	v_med3_f32 v245, v245, s97, v226
	v_med3_f32 v246, v246, s97, v226
	v_med3_f32 v247, v247, s97, v226
	v_med3_f32 v248, v248, s97, v226
	v_med3_f32 v249, v249, s97, v226
	v_med3_f32 v250, v250, s97, v226
	v_med3_f32 v251, v251, s97, v226
	v_mul_f32_e32 v244, 0xbfb8aa3b, v244
	v_mul_f32_e32 v245, 0xbfb8aa3b, v245
	v_mul_f32_e32 v246, 0xbfb8aa3b, v246
	v_mul_f32_e32 v247, 0xbfb8aa3b, v247
	v_mul_f32_e32 v248, 0xbfb8aa3b, v248
	v_mul_f32_e32 v249, 0xbfb8aa3b, v249
	v_mul_f32_e32 v250, 0xbfb8aa3b, v250
	v_mul_f32_e32 v251, 0xbfb8aa3b, v251
	v_exp_f32_e32 v244, v244
	v_exp_f32_e32 v245, v245
	v_exp_f32_e32 v246, v246
	v_exp_f32_e32 v247, v247
	v_exp_f32_e32 v248, v248
	v_exp_f32_e32 v249, v249
	v_exp_f32_e32 v250, v250
	v_exp_f32_e32 v251, v251
	v_add_f32_e32 v244, 1.0, v244
	v_add_f32_e32 v245, 1.0, v245
	v_add_f32_e32 v246, 1.0, v246
	v_add_f32_e32 v247, 1.0, v247
	v_add_f32_e32 v248, 1.0, v248
	v_add_f32_e32 v249, 1.0, v249
	v_add_f32_e32 v250, 1.0, v250
	v_add_f32_e32 v251, 1.0, v251
	v_pk_mul_f32 v[132:133], v[132:133], v[244:245]
	v_pk_mul_f32 v[134:135], v[134:135], v[246:247]
	v_pk_mul_f32 v[136:137], v[136:137], v[248:249]
	v_pk_mul_f32 v[138:139], v[138:139], v[250:251]
	v_pk_mul_f32 v[56:57], v[56:57], v[132:133]
	v_pk_mul_f32 v[58:59], v[58:59], v[134:135]
	v_pk_mul_f32 v[52:53], v[52:53], v[136:137]
	v_pk_mul_f32 v[54:55], v[54:55], v[138:139]
	s_waitcnt vmcnt(8)
;     static __device__ __forceinline__ float e1(float x) { return 1.0f + __expf(-fminf(fmaxf(x, -60.f), 60.f)); }
;     __device__ __forceinline__ void operator()(f32x4 (&acc)[2][2][4][2], const Unit& u, int wr, int wc, int fr, int fq) const {
;     ...
;                     const int col = col0 + bj * HALF;
;                     const bf16_t* gp = proj + (size_t)row * NP + C_GATE + u.z * D + col;
;                     const u32x4 ga = *(const u32x4*)gp;
;                     float sc[8];
;                     { float a[8]; unpack8(ga, a);
; #pragma unroll
;                       for (int j = 0; j < 8; ++j) sc[j] = __builtin_amdgcn_rcpf(e1(a[j])); }
;                     if (u.z < 2) { const u32x4 gb = *(const u32x4*)(gp + D); float b[8]; unpack8(gb, b);
; #pragma unroll
;                       for (int j = 0; j < 8; ++j) sc[j] *= e1(b[j]); }
;                     f32x4 v0 = acc[ai][bj][m][0], v1 = acc[ai][bj][m][1];
;                     v0[0] *= sc[0]; v0[1] *= sc[1]; v0[2] *= sc[2]; v0[3] *= sc[3]; v1[0] *= sc[4]; v1[1] *= sc[5]; v1[2] *= sc[6]; v1[3] *= sc[7];
;                     if (u.z < 2) { acc[ai][bj][m][0] = v0; acc[ai][bj][m][1] = v1; }
	v_lshlrev_b32_e32 v132, 16, v186
	v_and_b32_e32 v133, 0xffff0000, v186
	v_lshlrev_b32_e32 v134, 16, v187
	v_and_b32_e32 v135, 0xffff0000, v187
	v_lshlrev_b32_e32 v136, 16, v188
	v_and_b32_e32 v137, 0xffff0000, v188
	v_lshlrev_b32_e32 v138, 16, v189
	v_and_b32_e32 v139, 0xffff0000, v189
	v_lshlrev_b32_e32 v244, 16, v190
	v_and_b32_e32 v245, 0xffff0000, v190
	v_lshlrev_b32_e32 v246, 16, v191
	v_and_b32_e32 v247, 0xffff0000, v191
	v_lshlrev_b32_e32 v248, 16, v192
	v_and_b32_e32 v249, 0xffff0000, v192
	v_lshlrev_b32_e32 v250, 16, v193
	v_and_b32_e32 v251, 0xffff0000, v193
	v_med3_f32 v132, v132, s97, v226
	v_med3_f32 v133, v133, s97, v226
	v_med3_f32 v134, v134, s97, v226
	v_med3_f32 v135, v135, s97, v226
	v_med3_f32 v136, v136, s97, v226
	v_med3_f32 v137, v137, s97, v226
	v_med3_f32 v138, v138, s97, v226
	v_med3_f32 v139, v139, s97, v226
	v_mul_f32_e32 v132, 0xbfb8aa3b, v132
	v_mul_f32_e32 v133, 0xbfb8aa3b, v133
	v_mul_f32_e32 v134, 0xbfb8aa3b, v134
	v_mul_f32_e32 v135, 0xbfb8aa3b, v135
	v_mul_f32_e32 v136, 0xbfb8aa3b, v136
	v_mul_f32_e32 v137, 0xbfb8aa3b, v137
	v_mul_f32_e32 v138, 0xbfb8aa3b, v138
	v_mul_f32_e32 v139, 0xbfb8aa3b, v139
	v_exp_f32_e32 v132, v132
	v_exp_f32_e32 v133, v133
	v_exp_f32_e32 v134, v134
	v_exp_f32_e32 v135, v135
	v_exp_f32_e32 v136, v136
	v_exp_f32_e32 v137, v137
	v_exp_f32_e32 v138, v138
	v_exp_f32_e32 v139, v139
	v_add_f32_e32 v132, 1.0, v132
	v_add_f32_e32 v133, 1.0, v133
	v_add_f32_e32 v134, 1.0, v134
	v_add_f32_e32 v135, 1.0, v135
	v_add_f32_e32 v136, 1.0, v136
	v_add_f32_e32 v137, 1.0, v137
	v_add_f32_e32 v138, 1.0, v138
	v_add_f32_e32 v139, 1.0, v139
	v_rcp_f32_e32 v132, v132
	v_rcp_f32_e32 v133, v133
	v_rcp_f32_e32 v134, v134
	v_rcp_f32_e32 v135, v135
	v_rcp_f32_e32 v136, v136
	v_rcp_f32_e32 v137, v137
	v_rcp_f32_e32 v138, v138
	v_rcp_f32_e32 v139, v139
	v_med3_f32 v244, v244, s97, v226
	v_med3_f32 v245, v245, s97, v226
	v_med3_f32 v246, v246, s97, v226
	v_med3_f32 v247, v247, s97, v226
	v_med3_f32 v248, v248, s97, v226
	v_med3_f32 v249, v249, s97, v226
	v_med3_f32 v250, v250, s97, v226
	v_med3_f32 v251, v251, s97, v226
	v_mul_f32_e32 v244, 0xbfb8aa3b, v244
	v_mul_f32_e32 v245, 0xbfb8aa3b, v245
	v_mul_f32_e32 v246, 0xbfb8aa3b, v246
	v_mul_f32_e32 v247, 0xbfb8aa3b, v247
	v_mul_f32_e32 v248, 0xbfb8aa3b, v248
	v_mul_f32_e32 v249, 0xbfb8aa3b, v249
	v_mul_f32_e32 v250, 0xbfb8aa3b, v250
	v_mul_f32_e32 v251, 0xbfb8aa3b, v251
	v_exp_f32_e32 v244, v244
	v_exp_f32_e32 v245, v245
	v_exp_f32_e32 v246, v246
	v_exp_f32_e32 v247, v247
	v_exp_f32_e32 v248, v248
	v_exp_f32_e32 v249, v249
	v_exp_f32_e32 v250, v250
	v_exp_f32_e32 v251, v251
	v_add_f32_e32 v244, 1.0, v244
	v_add_f32_e32 v245, 1.0, v245
	v_add_f32_e32 v246, 1.0, v246
	v_add_f32_e32 v247, 1.0, v247
	v_add_f32_e32 v248, 1.0, v248
	v_add_f32_e32 v249, 1.0, v249
	v_add_f32_e32 v250, 1.0, v250
	v_add_f32_e32 v251, 1.0, v251
	v_pk_mul_f32 v[132:133], v[132:133], v[244:245]
	v_pk_mul_f32 v[134:135], v[134:135], v[246:247]
	v_pk_mul_f32 v[136:137], v[136:137], v[248:249]
	v_pk_mul_f32 v[138:139], v[138:139], v[250:251]
	v_pk_mul_f32 v[24:25], v[24:25], v[132:133]
	v_pk_mul_f32 v[26:27], v[26:27], v[134:135]
	v_pk_mul_f32 v[20:21], v[20:21], v[136:137]
	v_pk_mul_f32 v[22:23], v[22:23], v[138:139]
	s_waitcnt vmcnt(6)
	v_lshlrev_b32_e32 v132, 16, v194
	v_and_b32_e32 v133, 0xffff0000, v194
	v_lshlrev_b32_e32 v134, 16, v195
	v_and_b32_e32 v135, 0xffff0000, v195
	v_lshlrev_b32_e32 v136, 16, v196
	v_and_b32_e32 v137, 0xffff0000, v196
	v_lshlrev_b32_e32 v138, 16, v197
	v_and_b32_e32 v139, 0xffff0000, v197
	v_lshlrev_b32_e32 v244, 16, v198
	v_and_b32_e32 v245, 0xffff0000, v198
	v_lshlrev_b32_e32 v246, 16, v199
	v_and_b32_e32 v247, 0xffff0000, v199
	v_lshlrev_b32_e32 v248, 16, v200
	v_and_b32_e32 v249, 0xffff0000, v200
	v_lshlrev_b32_e32 v250, 16, v201
	v_and_b32_e32 v251, 0xffff0000, v201
	v_med3_f32 v132, v132, s97, v226
	v_med3_f32 v133, v133, s97, v226
	v_med3_f32 v134, v134, s97, v226
	v_med3_f32 v135, v135, s97, v226
	v_med3_f32 v136, v136, s97, v226
	v_med3_f32 v137, v137, s97, v226
	v_med3_f32 v138, v138, s97, v226
	v_med3_f32 v139, v139, s97, v226
	v_mul_f32_e32 v132, 0xbfb8aa3b, v132
	v_mul_f32_e32 v133, 0xbfb8aa3b, v133
	v_mul_f32_e32 v134, 0xbfb8aa3b, v134
	v_mul_f32_e32 v135, 0xbfb8aa3b, v135
	v_mul_f32_e32 v136, 0xbfb8aa3b, v136
	v_mul_f32_e32 v137, 0xbfb8aa3b, v137
	v_mul_f32_e32 v138, 0xbfb8aa3b, v138
	v_mul_f32_e32 v139, 0xbfb8aa3b, v139
	v_exp_f32_e32 v132, v132
	v_exp_f32_e32 v133, v133
	v_exp_f32_e32 v134, v134
	v_exp_f32_e32 v135, v135
	v_exp_f32_e32 v136, v136
	v_exp_f32_e32 v137, v137
	v_exp_f32_e32 v138, v138
	v_exp_f32_e32 v139, v139
	v_add_f32_e32 v132, 1.0, v132
	v_add_f32_e32 v133, 1.0, v133
	v_add_f32_e32 v134, 1.0, v134
	v_add_f32_e32 v135, 1.0, v135
	v_add_f32_e32 v136, 1.0, v136
	v_add_f32_e32 v137, 1.0, v137
	v_add_f32_e32 v138, 1.0, v138
	v_add_f32_e32 v139, 1.0, v139
	v_rcp_f32_e32 v132, v132
	v_rcp_f32_e32 v133, v133
	v_rcp_f32_e32 v134, v134
	v_rcp_f32_e32 v135, v135
	v_rcp_f32_e32 v136, v136
	v_rcp_f32_e32 v137, v137
	v_rcp_f32_e32 v138, v138
	v_rcp_f32_e32 v139, v139
	v_med3_f32 v244, v244, s97, v226
	v_med3_f32 v245, v245, s97, v226
	v_med3_f32 v246, v246, s97, v226
	v_med3_f32 v247, v247, s97, v226
	v_med3_f32 v248, v248, s97, v226
	v_med3_f32 v249, v249, s97, v226
	v_med3_f32 v250, v250, s97, v226
	v_med3_f32 v251, v251, s97, v226
	v_mul_f32_e32 v244, 0xbfb8aa3b, v244
	v_mul_f32_e32 v245, 0xbfb8aa3b, v245
	v_mul_f32_e32 v246, 0xbfb8aa3b, v246
	v_mul_f32_e32 v247, 0xbfb8aa3b, v247
	v_mul_f32_e32 v248, 0xbfb8aa3b, v248
	v_mul_f32_e32 v249, 0xbfb8aa3b, v249
	v_mul_f32_e32 v250, 0xbfb8aa3b, v250
	v_mul_f32_e32 v251, 0xbfb8aa3b, v251
	v_exp_f32_e32 v244, v244
	v_exp_f32_e32 v245, v245
	v_exp_f32_e32 v246, v246
	v_exp_f32_e32 v247, v247
	v_exp_f32_e32 v248, v248
	v_exp_f32_e32 v249, v249
	v_exp_f32_e32 v250, v250
	v_exp_f32_e32 v251, v251
	v_add_f32_e32 v244, 1.0, v244
	v_add_f32_e32 v245, 1.0, v245
	v_add_f32_e32 v246, 1.0, v246
	v_add_f32_e32 v247, 1.0, v247
	v_add_f32_e32 v248, 1.0, v248
	v_add_f32_e32 v249, 1.0, v249
	v_add_f32_e32 v250, 1.0, v250
	v_add_f32_e32 v251, 1.0, v251
	v_pk_mul_f32 v[132:133], v[132:133], v[244:245]
	v_pk_mul_f32 v[134:135], v[134:135], v[246:247]
	v_pk_mul_f32 v[136:137], v[136:137], v[248:249]
	v_pk_mul_f32 v[138:139], v[138:139], v[250:251]
	v_pk_mul_f32 v[48:49], v[48:49], v[132:133]
	v_pk_mul_f32 v[50:51], v[50:51], v[134:135]
	v_pk_mul_f32 v[44:45], v[44:45], v[136:137]
	v_pk_mul_f32 v[46:47], v[46:47], v[138:139]
	s_waitcnt vmcnt(4)
;     static __device__ __forceinline__ float e1(float x) { return 1.0f + __expf(-fminf(fmaxf(x, -60.f), 60.f)); }
;     __device__ __forceinline__ void operator()(f32x4 (&acc)[2][2][4][2], const Unit& u, int wr, int wc, int fr, int fq) const {
;     ...
;                     const int col = col0 + bj * HALF;
;                     const bf16_t* gp = proj + (size_t)row * NP + C_GATE + u.z * D + col;
;                     const u32x4 ga = *(const u32x4*)gp;
;                     float sc[8];
;                     { float a[8]; unpack8(ga, a);
; #pragma unroll
;                       for (int j = 0; j < 8; ++j) sc[j] = __builtin_amdgcn_rcpf(e1(a[j])); }
;                     if (u.z < 2) { const u32x4 gb = *(const u32x4*)(gp + D); float b[8]; unpack8(gb, b);
; #pragma unroll
;                       for (int j = 0; j < 8; ++j) sc[j] *= e1(b[j]); }
;                     f32x4 v0 = acc[ai][bj][m][0], v1 = acc[ai][bj][m][1];
;                     v0[0] *= sc[0]; v0[1] *= sc[1]; v0[2] *= sc[2]; v0[3] *= sc[3]; v1[0] *= sc[4]; v1[1] *= sc[5]; v1[2] *= sc[6]; v1[3] *= sc[7];
;                     if (u.z < 2) { acc[ai][bj][m][0] = v0; acc[ai][bj][m][1] = v1; }
	v_lshlrev_b32_e32 v132, 16, v206
	v_and_b32_e32 v133, 0xffff0000, v206
	v_lshlrev_b32_e32 v134, 16, v207
	v_and_b32_e32 v135, 0xffff0000, v207
	v_lshlrev_b32_e32 v136, 16, v208
	v_and_b32_e32 v137, 0xffff0000, v208
	v_lshlrev_b32_e32 v138, 16, v209
	v_and_b32_e32 v139, 0xffff0000, v209
	v_lshlrev_b32_e32 v244, 16, v210
	v_and_b32_e32 v245, 0xffff0000, v210
	v_lshlrev_b32_e32 v246, 16, v211
	v_and_b32_e32 v247, 0xffff0000, v211
	v_lshlrev_b32_e32 v248, 16, v212
	v_and_b32_e32 v249, 0xffff0000, v212
	v_lshlrev_b32_e32 v250, 16, v213
	v_and_b32_e32 v251, 0xffff0000, v213
	v_med3_f32 v132, v132, s97, v226
	v_med3_f32 v133, v133, s97, v226
	v_med3_f32 v134, v134, s97, v226
	v_med3_f32 v135, v135, s97, v226
	v_med3_f32 v136, v136, s97, v226
	v_med3_f32 v137, v137, s97, v226
	v_med3_f32 v138, v138, s97, v226
	v_med3_f32 v139, v139, s97, v226
	v_mul_f32_e32 v132, 0xbfb8aa3b, v132
	v_mul_f32_e32 v133, 0xbfb8aa3b, v133
	v_mul_f32_e32 v134, 0xbfb8aa3b, v134
	v_mul_f32_e32 v135, 0xbfb8aa3b, v135
	v_mul_f32_e32 v136, 0xbfb8aa3b, v136
	v_mul_f32_e32 v137, 0xbfb8aa3b, v137
	v_mul_f32_e32 v138, 0xbfb8aa3b, v138
	v_mul_f32_e32 v139, 0xbfb8aa3b, v139
	v_exp_f32_e32 v132, v132
	v_exp_f32_e32 v133, v133
	v_exp_f32_e32 v134, v134
	v_exp_f32_e32 v135, v135
	v_exp_f32_e32 v136, v136
	v_exp_f32_e32 v137, v137
	v_exp_f32_e32 v138, v138
	v_exp_f32_e32 v139, v139
	v_add_f32_e32 v132, 1.0, v132
	v_add_f32_e32 v133, 1.0, v133
	v_add_f32_e32 v134, 1.0, v134
	v_add_f32_e32 v135, 1.0, v135
	v_add_f32_e32 v136, 1.0, v136
	v_add_f32_e32 v137, 1.0, v137
	v_add_f32_e32 v138, 1.0, v138
	v_add_f32_e32 v139, 1.0, v139
	v_rcp_f32_e32 v132, v132
	v_rcp_f32_e32 v133, v133
	v_rcp_f32_e32 v134, v134
	v_rcp_f32_e32 v135, v135
	v_rcp_f32_e32 v136, v136
	v_rcp_f32_e32 v137, v137
	v_rcp_f32_e32 v138, v138
	v_rcp_f32_e32 v139, v139
	v_med3_f32 v244, v244, s97, v226
	v_med3_f32 v245, v245, s97, v226
	v_med3_f32 v246, v246, s97, v226
	v_med3_f32 v247, v247, s97, v226
	v_med3_f32 v248, v248, s97, v226
	v_med3_f32 v249, v249, s97, v226
	v_med3_f32 v250, v250, s97, v226
	v_med3_f32 v251, v251, s97, v226
	v_mul_f32_e32 v244, 0xbfb8aa3b, v244
	v_mul_f32_e32 v245, 0xbfb8aa3b, v245
	v_mul_f32_e32 v246, 0xbfb8aa3b, v246
	v_mul_f32_e32 v247, 0xbfb8aa3b, v247
	v_mul_f32_e32 v248, 0xbfb8aa3b, v248
	v_mul_f32_e32 v249, 0xbfb8aa3b, v249
	v_mul_f32_e32 v250, 0xbfb8aa3b, v250
	v_mul_f32_e32 v251, 0xbfb8aa3b, v251
	v_exp_f32_e32 v244, v244
	v_exp_f32_e32 v245, v245
	v_exp_f32_e32 v246, v246
	v_exp_f32_e32 v247, v247
	v_exp_f32_e32 v248, v248
	v_exp_f32_e32 v249, v249
	v_exp_f32_e32 v250, v250
	v_exp_f32_e32 v251, v251
	v_add_f32_e32 v244, 1.0, v244
	v_add_f32_e32 v245, 1.0, v245
	v_add_f32_e32 v246, 1.0, v246
	v_add_f32_e32 v247, 1.0, v247
	v_add_f32_e32 v248, 1.0, v248
	v_add_f32_e32 v249, 1.0, v249
	v_add_f32_e32 v250, 1.0, v250
	v_add_f32_e32 v251, 1.0, v251
	v_pk_mul_f32 v[132:133], v[132:133], v[244:245]
	v_pk_mul_f32 v[134:135], v[134:135], v[246:247]
	v_pk_mul_f32 v[136:137], v[136:137], v[248:249]
	v_pk_mul_f32 v[138:139], v[138:139], v[250:251]
	v_pk_mul_f32 v[16:17], v[16:17], v[132:133]
	v_pk_mul_f32 v[18:19], v[18:19], v[134:135]
	v_pk_mul_f32 v[12:13], v[12:13], v[136:137]
	v_pk_mul_f32 v[14:15], v[14:15], v[138:139]
	s_waitcnt vmcnt(2)
	v_lshlrev_b32_e32 v132, 16, v228
	v_and_b32_e32 v133, 0xffff0000, v228
	v_lshlrev_b32_e32 v134, 16, v229
	v_and_b32_e32 v135, 0xffff0000, v229
	v_lshlrev_b32_e32 v136, 16, v230
	v_and_b32_e32 v137, 0xffff0000, v230
	v_lshlrev_b32_e32 v138, 16, v231
	v_and_b32_e32 v139, 0xffff0000, v231
	v_lshlrev_b32_e32 v244, 16, v232
	v_and_b32_e32 v245, 0xffff0000, v232
	v_lshlrev_b32_e32 v246, 16, v233
	v_and_b32_e32 v247, 0xffff0000, v233
	v_lshlrev_b32_e32 v248, 16, v234
	v_and_b32_e32 v249, 0xffff0000, v234
	v_lshlrev_b32_e32 v250, 16, v235
	v_and_b32_e32 v251, 0xffff0000, v235
	v_med3_f32 v132, v132, s97, v226
	v_med3_f32 v133, v133, s97, v226
	v_med3_f32 v134, v134, s97, v226
	v_med3_f32 v135, v135, s97, v226
	v_med3_f32 v136, v136, s97, v226
	v_med3_f32 v137, v137, s97, v226
	v_med3_f32 v138, v138, s97, v226
	v_med3_f32 v139, v139, s97, v226
	v_mul_f32_e32 v132, 0xbfb8aa3b, v132
	v_mul_f32_e32 v133, 0xbfb8aa3b, v133
	v_mul_f32_e32 v134, 0xbfb8aa3b, v134
	v_mul_f32_e32 v135, 0xbfb8aa3b, v135
	v_mul_f32_e32 v136, 0xbfb8aa3b, v136
	v_mul_f32_e32 v137, 0xbfb8aa3b, v137
	v_mul_f32_e32 v138, 0xbfb8aa3b, v138
	v_mul_f32_e32 v139, 0xbfb8aa3b, v139
	v_exp_f32_e32 v132, v132
	v_exp_f32_e32 v133, v133
	v_exp_f32_e32 v134, v134
	v_exp_f32_e32 v135, v135
	v_exp_f32_e32 v136, v136
	v_exp_f32_e32 v137, v137
	v_exp_f32_e32 v138, v138
	v_exp_f32_e32 v139, v139
	v_add_f32_e32 v132, 1.0, v132
	v_add_f32_e32 v133, 1.0, v133
	v_add_f32_e32 v134, 1.0, v134
	v_add_f32_e32 v135, 1.0, v135
	v_add_f32_e32 v136, 1.0, v136
	v_add_f32_e32 v137, 1.0, v137
	v_add_f32_e32 v138, 1.0, v138
	v_add_f32_e32 v139, 1.0, v139
	v_rcp_f32_e32 v132, v132
	v_rcp_f32_e32 v133, v133
	v_rcp_f32_e32 v134, v134
	v_rcp_f32_e32 v135, v135
	v_rcp_f32_e32 v136, v136
	v_rcp_f32_e32 v137, v137
	v_rcp_f32_e32 v138, v138
	v_rcp_f32_e32 v139, v139
	v_med3_f32 v244, v244, s97, v226
	v_med3_f32 v245, v245, s97, v226
	v_med3_f32 v246, v246, s97, v226
	v_med3_f32 v247, v247, s97, v226
	v_med3_f32 v248, v248, s97, v226
	v_med3_f32 v249, v249, s97, v226
	v_med3_f32 v250, v250, s97, v226
	v_med3_f32 v251, v251, s97, v226
	v_mul_f32_e32 v244, 0xbfb8aa3b, v244
	v_mul_f32_e32 v245, 0xbfb8aa3b, v245
	v_mul_f32_e32 v246, 0xbfb8aa3b, v246
	v_mul_f32_e32 v247, 0xbfb8aa3b, v247
	v_mul_f32_e32 v248, 0xbfb8aa3b, v248
	v_mul_f32_e32 v249, 0xbfb8aa3b, v249
	v_mul_f32_e32 v250, 0xbfb8aa3b, v250
	v_mul_f32_e32 v251, 0xbfb8aa3b, v251
	v_exp_f32_e32 v244, v244
	v_exp_f32_e32 v245, v245
	v_exp_f32_e32 v246, v246
	v_exp_f32_e32 v247, v247
	v_exp_f32_e32 v248, v248
	v_exp_f32_e32 v249, v249
	v_exp_f32_e32 v250, v250
	v_exp_f32_e32 v251, v251
	v_add_f32_e32 v244, 1.0, v244
	v_add_f32_e32 v245, 1.0, v245
	v_add_f32_e32 v246, 1.0, v246
	v_add_f32_e32 v247, 1.0, v247
	v_add_f32_e32 v248, 1.0, v248
	v_add_f32_e32 v249, 1.0, v249
	v_add_f32_e32 v250, 1.0, v250
	v_add_f32_e32 v251, 1.0, v251
	v_pk_mul_f32 v[132:133], v[132:133], v[244:245]
	v_pk_mul_f32 v[134:135], v[134:135], v[246:247]
	v_pk_mul_f32 v[136:137], v[136:137], v[248:249]
	v_pk_mul_f32 v[138:139], v[138:139], v[250:251]
	v_pk_mul_f32 v[40:41], v[40:41], v[132:133]
	v_pk_mul_f32 v[42:43], v[42:43], v[134:135]
	v_pk_mul_f32 v[36:37], v[36:37], v[136:137]
	v_pk_mul_f32 v[38:39], v[38:39], v[138:139]
	s_waitcnt vmcnt(0)
; __device__ __forceinline__ unsigned pk2(float lo, float hi) { f32x2_t v = {lo, hi}; bf16x2_t b = __builtin_convertvector(v, bf16x2_t); return __builtin_bit_cast(unsigned, b); }
;     static __device__ __forceinline__ float e1(float x) { return 1.0f + __expf(-fminf(fmaxf(x, -60.f), 60.f)); }
;     __device__ __forceinline__ void operator()(f32x4 (&acc)[2][2][4][2], const Unit& u, int wr, int wc, int fr, int fq) const {
;     ...
;                     const int col = col0 + bj * HALF;
;                     const bf16_t* gp = proj + (size_t)row * NP + C_GATE + u.z * D + col;
;                     const u32x4 ga = *(const u32x4*)gp;
;                     float sc[8];
;                     { float a[8]; unpack8(ga, a);
; #pragma unroll
;                       for (int j = 0; j < 8; ++j) sc[j] = __builtin_amdgcn_rcpf(e1(a[j])); }
;                     if (u.z < 2) { const u32x4 gb = *(const u32x4*)(gp + D); float b[8]; unpack8(gb, b);
; #pragma unroll
;                       for (int j = 0; j < 8; ++j) sc[j] *= e1(b[j]); }
;                     f32x4 v0 = acc[ai][bj][m][0], v1 = acc[ai][bj][m][1];
;                     v0[0] *= sc[0]; v0[1] *= sc[1]; v0[2] *= sc[2]; v0[3] *= sc[3]; v1[0] *= sc[4]; v1[1] *= sc[5]; v1[2] *= sc[6]; v1[3] *= sc[7];
;                     if (u.z < 2) { acc[ai][bj][m][0] = v0; acc[ai][bj][m][1] = v1; }
;                     else { u32x4 w; w.x = pk2(v0[0], v0[1]); w.y = pk2(v0[2], v0[3]); w.z = pk2(v1[0], v1[1]); w.w = pk2(v1[2], v1[3]); *(u32x4*)(YB + (size_t)row * D + col) = w; }
	v_lshlrev_b32_e32 v132, 16, v236
	v_and_b32_e32 v133, 0xffff0000, v236
	v_lshlrev_b32_e32 v134, 16, v237
	v_and_b32_e32 v135, 0xffff0000, v237
	v_lshlrev_b32_e32 v136, 16, v238
	v_and_b32_e32 v137, 0xffff0000, v238
	v_lshlrev_b32_e32 v138, 16, v239
	v_and_b32_e32 v139, 0xffff0000, v239
	v_lshlrev_b32_e32 v244, 16, v240
	v_and_b32_e32 v245, 0xffff0000, v240
	v_lshlrev_b32_e32 v246, 16, v241
	v_and_b32_e32 v247, 0xffff0000, v241
	v_lshlrev_b32_e32 v248, 16, v242
	v_and_b32_e32 v249, 0xffff0000, v242
	v_lshlrev_b32_e32 v250, 16, v243
	v_and_b32_e32 v251, 0xffff0000, v243
	v_med3_f32 v132, v132, s97, v226
	v_med3_f32 v133, v133, s97, v226
	v_med3_f32 v134, v134, s97, v226
	v_med3_f32 v135, v135, s97, v226
	v_med3_f32 v136, v136, s97, v226
	v_med3_f32 v137, v137, s97, v226
	v_med3_f32 v138, v138, s97, v226
	v_med3_f32 v139, v139, s97, v226
	v_mul_f32_e32 v132, 0xbfb8aa3b, v132
	v_mul_f32_e32 v133, 0xbfb8aa3b, v133
	v_mul_f32_e32 v134, 0xbfb8aa3b, v134
	v_mul_f32_e32 v135, 0xbfb8aa3b, v135
	v_mul_f32_e32 v136, 0xbfb8aa3b, v136
	v_mul_f32_e32 v137, 0xbfb8aa3b, v137
	v_mul_f32_e32 v138, 0xbfb8aa3b, v138
	v_mul_f32_e32 v139, 0xbfb8aa3b, v139
	v_exp_f32_e32 v132, v132
	v_exp_f32_e32 v133, v133
	v_exp_f32_e32 v134, v134
	v_exp_f32_e32 v135, v135
	v_exp_f32_e32 v136, v136
	v_exp_f32_e32 v137, v137
	v_exp_f32_e32 v138, v138
	v_exp_f32_e32 v139, v139
	v_add_f32_e32 v132, 1.0, v132
	v_add_f32_e32 v133, 1.0, v133
	v_add_f32_e32 v134, 1.0, v134
	v_add_f32_e32 v135, 1.0, v135
	v_add_f32_e32 v136, 1.0, v136
	v_add_f32_e32 v137, 1.0, v137
	v_add_f32_e32 v138, 1.0, v138
	v_add_f32_e32 v139, 1.0, v139
	v_rcp_f32_e32 v132, v132
	v_rcp_f32_e32 v133, v133
	v_rcp_f32_e32 v134, v134
	v_rcp_f32_e32 v135, v135
	v_rcp_f32_e32 v136, v136
	v_rcp_f32_e32 v137, v137
	v_rcp_f32_e32 v138, v138
	v_rcp_f32_e32 v139, v139
	v_med3_f32 v244, v244, s97, v226
	v_med3_f32 v245, v245, s97, v226
	v_med3_f32 v246, v246, s97, v226
	v_med3_f32 v247, v247, s97, v226
	v_med3_f32 v248, v248, s97, v226
	v_med3_f32 v249, v249, s97, v226
	v_med3_f32 v250, v250, s97, v226
	v_med3_f32 v251, v251, s97, v226
	v_mul_f32_e32 v244, 0xbfb8aa3b, v244
	v_mul_f32_e32 v245, 0xbfb8aa3b, v245
	v_mul_f32_e32 v246, 0xbfb8aa3b, v246
	v_mul_f32_e32 v247, 0xbfb8aa3b, v247
	v_mul_f32_e32 v248, 0xbfb8aa3b, v248
	v_mul_f32_e32 v249, 0xbfb8aa3b, v249
	v_mul_f32_e32 v250, 0xbfb8aa3b, v250
	v_mul_f32_e32 v251, 0xbfb8aa3b, v251
	v_exp_f32_e32 v244, v244
	v_exp_f32_e32 v245, v245
	v_exp_f32_e32 v246, v246
	v_exp_f32_e32 v247, v247
	v_exp_f32_e32 v248, v248
	v_exp_f32_e32 v249, v249
	v_exp_f32_e32 v250, v250
	v_exp_f32_e32 v251, v251
	v_add_f32_e32 v244, 1.0, v244
	v_add_f32_e32 v245, 1.0, v245
	v_add_f32_e32 v246, 1.0, v246
	v_add_f32_e32 v247, 1.0, v247
	v_add_f32_e32 v248, 1.0, v248
	v_add_f32_e32 v249, 1.0, v249
	v_add_f32_e32 v250, 1.0, v250
	v_add_f32_e32 v251, 1.0, v251
	v_pk_mul_f32 v[132:133], v[132:133], v[244:245]
	v_pk_mul_f32 v[134:135], v[134:135], v[246:247]
	v_pk_mul_f32 v[136:137], v[136:137], v[248:249]
	v_pk_mul_f32 v[138:139], v[138:139], v[250:251]
	v_pk_mul_f32 v[8:9], v[8:9], v[132:133]
	v_pk_mul_f32 v[10:11], v[10:11], v[134:135]
	v_pk_mul_f32 v[4:5], v[4:5], v[136:137]
	v_pk_mul_f32 v[6:7], v[6:7], v[138:139]
	s_mov_b64 s[40:41], -1
	s_mov_b64 s[42:43], 0
	s_branch .Lp3_done
.Lp3_store:
	s_mov_b64 s[8:9], 0x0
	v_lshl_add_u64 v[156:157], v[152:153], 0, s[8:9]
	global_load_dwordx4 v[162:165], v[156:157], off offset:-4096
	s_mov_b64 s[8:9], 0x0
	v_lshl_add_u64 v[156:157], v[152:153], 0, s[8:9]
	global_load_dwordx4 v[170:173], v[156:157], off offset:-3840
	s_mov_b64 s[8:9], 0x88000
	v_lshl_add_u64 v[156:157], v[152:153], 0, s[8:9]
	global_load_dwordx4 v[178:181], v[156:157], off offset:-4096
	s_mov_b64 s[8:9], 0x88000
	v_lshl_add_u64 v[156:157], v[152:153], 0, s[8:9]
	global_load_dwordx4 v[186:189], v[156:157], off offset:-3840
	s_mov_b64 s[8:9], 0x110000
	v_lshl_add_u64 v[156:157], v[152:153], 0, s[8:9]
	global_load_dwordx4 v[194:197], v[156:157], off offset:-4096
	s_mov_b64 s[8:9], 0x110000
	v_lshl_add_u64 v[156:157], v[152:153], 0, s[8:9]
	global_load_dwordx4 v[206:209], v[156:157], off offset:-3840
	s_mov_b64 s[8:9], 0x198000
	v_lshl_add_u64 v[156:157], v[152:153], 0, s[8:9]
	global_load_dwordx4 v[228:231], v[156:157], off offset:-4096
	s_mov_b64 s[8:9], 0x198000
	v_lshl_add_u64 v[156:157], v[152:153], 0, s[8:9]
	global_load_dwordx4 v[236:239], v[156:157], off offset:-3840
	s_waitcnt vmcnt(7)
	v_lshlrev_b32_e32 v132, 16, v162
	v_and_b32_e32 v133, 0xffff0000, v162
	v_lshlrev_b32_e32 v134, 16, v163
	v_and_b32_e32 v135, 0xffff0000, v163
	v_lshlrev_b32_e32 v136, 16, v164
	v_and_b32_e32 v137, 0xffff0000, v164
	v_lshlrev_b32_e32 v138, 16, v165
	v_and_b32_e32 v139, 0xffff0000, v165
	s_mov_b64 s[8:9], 0x440000
	v_lshl_add_u64 v[156:157], v[152:153], 0, s[8:9]
	global_load_dwordx4 v[162:165], v[156:157], off offset:-4096
	v_med3_f32 v132, v132, s97, v226
	v_med3_f32 v133, v133, s97, v226
	v_med3_f32 v134, v134, s97, v226
	v_med3_f32 v135, v135, s97, v226
	v_med3_f32 v136, v136, s97, v226
	v_med3_f32 v137, v137, s97, v226
	v_med3_f32 v138, v138, s97, v226
	v_med3_f32 v139, v139, s97, v226
	v_mul_f32_e32 v132, 0xbfb8aa3b, v132
	v_mul_f32_e32 v133, 0xbfb8aa3b, v133
	v_mul_f32_e32 v134, 0xbfb8aa3b, v134
	v_mul_f32_e32 v135, 0xbfb8aa3b, v135
	v_mul_f32_e32 v136, 0xbfb8aa3b, v136
	v_mul_f32_e32 v137, 0xbfb8aa3b, v137
	v_mul_f32_e32 v138, 0xbfb8aa3b, v138
	v_mul_f32_e32 v139, 0xbfb8aa3b, v139
	v_exp_f32_e32 v132, v132
	v_exp_f32_e32 v133, v133
	v_exp_f32_e32 v134, v134
	v_exp_f32_e32 v135, v135
	v_exp_f32_e32 v136, v136
	v_exp_f32_e32 v137, v137
	v_exp_f32_e32 v138, v138
	v_exp_f32_e32 v139, v139
	v_add_f32_e32 v132, 1.0, v132
	v_add_f32_e32 v133, 1.0, v133
	v_add_f32_e32 v134, 1.0, v134
	v_add_f32_e32 v135, 1.0, v135
	v_add_f32_e32 v136, 1.0, v136
	v_add_f32_e32 v137, 1.0, v137
	v_add_f32_e32 v138, 1.0, v138
	v_add_f32_e32 v139, 1.0, v139
	v_rcp_f32_e32 v132, v132
	v_rcp_f32_e32 v133, v133
	v_rcp_f32_e32 v134, v134
	v_rcp_f32_e32 v135, v135
	v_rcp_f32_e32 v136, v136
	v_rcp_f32_e32 v137, v137
	v_rcp_f32_e32 v138, v138
	v_rcp_f32_e32 v139, v139
	v_pk_mul_f32 v[132:133], v[128:129], v[132:133]
	v_pk_mul_f32 v[134:135], v[130:131], v[134:135]
	v_pk_mul_f32 v[136:137], v[124:125], v[136:137]
	v_pk_mul_f32 v[138:139], v[126:127], v[138:139]
	v_cvt_pk_bf16_f32 v244, v132, v133
	v_cvt_pk_bf16_f32 v245, v134, v135
	v_cvt_pk_bf16_f32 v246, v136, v137
	v_cvt_pk_bf16_f32 v247, v138, v139
	s_mov_b64 s[8:9], 0x0
	v_lshl_add_u64 v[156:157], v[154:155], 0, s[8:9]
	global_store_dwordx4 v[156:157], v[244:247], off offset:0
	s_waitcnt vmcnt(8)
; __device__ __forceinline__ unsigned pk2(float lo, float hi) { f32x2_t v = {lo, hi}; bf16x2_t b = __builtin_convertvector(v, bf16x2_t); return __builtin_bit_cast(unsigned, b); }
;     static __device__ __forceinline__ float e1(float x) { return 1.0f + __expf(-fminf(fmaxf(x, -60.f), 60.f)); }
;     __device__ __forceinline__ void operator()(f32x4 (&acc)[2][2][4][2], const Unit& u, int wr, int wc, int fr, int fq) const {
;         const int row0 = u.pm * BM + wr * 64 + fr, col0 = u.pn * BM + wc * 32 + 8 * fq;
; #pragma unroll
;         for (int ai = 0; ai < 2; ++ai)
; #pragma unroll
;             for (int m = 0; m < 4; ++m) {
;                 const int row = row0 + ai * HALF + m * 16;
; #pragma unroll
;                 for (int bj = 0; bj < 2; ++bj) {
;                     const int col = col0 + bj * HALF;
;                     const bf16_t* gp = proj + (size_t)row * NP + C_GATE + u.z * D + col;
;                     const u32x4 ga = *(const u32x4*)gp;
;                     float sc[8];
;                     { float a[8]; unpack8(ga, a);
; #pragma unroll
;                       for (int j = 0; j < 8; ++j) sc[j] = __builtin_amdgcn_rcpf(e1(a[j])); }
;                     if (u.z < 2) { const u32x4 gb = *(const u32x4*)(gp + D); float b[8]; unpack8(gb, b);
; #pragma unroll
;                       for (int j = 0; j < 8; ++j) sc[j] *= e1(b[j]); }
;                     f32x4 v0 = acc[ai][bj][m][0], v1 = acc[ai][bj][m][1];
;                     v0[0] *= sc[0]; v0[1] *= sc[1]; v0[2] *= sc[2]; v0[3] *= sc[3]; v1[0] *= sc[4]; v1[1] *= sc[5]; v1[2] *= sc[6]; v1[3] *= sc[7];
;                     if (u.z < 2) { acc[ai][bj][m][0] = v0; acc[ai][bj][m][1] = v1; }
;                     else { u32x4 w; w.x = pk2(v0[0], v0[1]); w.y = pk2(v0[2], v0[3]); w.z = pk2(v1[0], v1[1]); w.w = pk2(v1[2], v1[3]); *(u32x4*)(YB + (size_t)row * D + col) = w; }
	v_lshlrev_b32_e32 v132, 16, v170
	v_and_b32_e32 v133, 0xffff0000, v170
	v_lshlrev_b32_e32 v134, 16, v171
	v_and_b32_e32 v135, 0xffff0000, v171
	v_lshlrev_b32_e32 v136, 16, v172
	v_and_b32_e32 v137, 0xffff0000, v172
	v_lshlrev_b32_e32 v138, 16, v173
	v_and_b32_e32 v139, 0xffff0000, v173
	s_mov_b64 s[8:9], 0x440000
	v_lshl_add_u64 v[156:157], v[152:153], 0, s[8:9]
	global_load_dwordx4 v[170:173], v[156:157], off offset:-3840
	v_med3_f32 v132, v132, s97, v226
	v_med3_f32 v133, v133, s97, v226
	v_med3_f32 v134, v134, s97, v226
	v_med3_f32 v135, v135, s97, v226
	v_med3_f32 v136, v136, s97, v226
	v_med3_f32 v137, v137, s97, v226
	v_med3_f32 v138, v138, s97, v226
	v_med3_f32 v139, v139, s97, v226
	v_mul_f32_e32 v132, 0xbfb8aa3b, v132
	v_mul_f32_e32 v133, 0xbfb8aa3b, v133
	v_mul_f32_e32 v134, 0xbfb8aa3b, v134
	v_mul_f32_e32 v135, 0xbfb8aa3b, v135
	v_mul_f32_e32 v136, 0xbfb8aa3b, v136
	v_mul_f32_e32 v137, 0xbfb8aa3b, v137
	v_mul_f32_e32 v138, 0xbfb8aa3b, v138
	v_mul_f32_e32 v139, 0xbfb8aa3b, v139
	v_exp_f32_e32 v132, v132
	v_exp_f32_e32 v133, v133
	v_exp_f32_e32 v134, v134
	v_exp_f32_e32 v135, v135
	v_exp_f32_e32 v136, v136
	v_exp_f32_e32 v137, v137
	v_exp_f32_e32 v138, v138
	v_exp_f32_e32 v139, v139
	v_add_f32_e32 v132, 1.0, v132
	v_add_f32_e32 v133, 1.0, v133
	v_add_f32_e32 v134, 1.0, v134
	v_add_f32_e32 v135, 1.0, v135
	v_add_f32_e32 v136, 1.0, v136
	v_add_f32_e32 v137, 1.0, v137
	v_add_f32_e32 v138, 1.0, v138
	v_add_f32_e32 v139, 1.0, v139
	v_rcp_f32_e32 v132, v132
	v_rcp_f32_e32 v133, v133
	v_rcp_f32_e32 v134, v134
	v_rcp_f32_e32 v135, v135
	v_rcp_f32_e32 v136, v136
	v_rcp_f32_e32 v137, v137
	v_rcp_f32_e32 v138, v138
	v_rcp_f32_e32 v139, v139
	v_pk_mul_f32 v[132:133], v[96:97], v[132:133]
	v_pk_mul_f32 v[134:135], v[98:99], v[134:135]
	v_pk_mul_f32 v[136:137], v[92:93], v[136:137]
	v_pk_mul_f32 v[138:139], v[94:95], v[138:139]
	v_cvt_pk_bf16_f32 v248, v132, v133
	v_cvt_pk_bf16_f32 v249, v134, v135
	v_cvt_pk_bf16_f32 v250, v136, v137
	v_cvt_pk_bf16_f32 v251, v138, v139
	s_mov_b64 s[8:9], 0x0
	v_lshl_add_u64 v[156:157], v[154:155], 0, s[8:9]
	global_store_dwordx4 v[156:157], v[248:251], off offset:256
	s_waitcnt vmcnt(9)
	v_lshlrev_b32_e32 v132, 16, v178
	v_and_b32_e32 v133, 0xffff0000, v178
	v_lshlrev_b32_e32 v134, 16, v179
	v_and_b32_e32 v135, 0xffff0000, v179
	v_lshlrev_b32_e32 v136, 16, v180
	v_and_b32_e32 v137, 0xffff0000, v180
	v_lshlrev_b32_e32 v138, 16, v181
	v_and_b32_e32 v139, 0xffff0000, v181
	s_mov_b64 s[8:9], 0x4c8000
	v_lshl_add_u64 v[156:157], v[152:153], 0, s[8:9]
	global_load_dwordx4 v[178:181], v[156:157], off offset:-4096
	v_med3_f32 v132, v132, s97, v226
	v_med3_f32 v133, v133, s97, v226
	v_med3_f32 v134, v134, s97, v226
	v_med3_f32 v135, v135, s97, v226
	v_med3_f32 v136, v136, s97, v226
	v_med3_f32 v137, v137, s97, v226
	v_med3_f32 v138, v138, s97, v226
	v_med3_f32 v139, v139, s97, v226
	v_mul_f32_e32 v132, 0xbfb8aa3b, v132
	v_mul_f32_e32 v133, 0xbfb8aa3b, v133
	v_mul_f32_e32 v134, 0xbfb8aa3b, v134
	v_mul_f32_e32 v135, 0xbfb8aa3b, v135
	v_mul_f32_e32 v136, 0xbfb8aa3b, v136
	v_mul_f32_e32 v137, 0xbfb8aa3b, v137
	v_mul_f32_e32 v138, 0xbfb8aa3b, v138
	v_mul_f32_e32 v139, 0xbfb8aa3b, v139
	v_exp_f32_e32 v132, v132
	v_exp_f32_e32 v133, v133
	v_exp_f32_e32 v134, v134
	v_exp_f32_e32 v135, v135
	v_exp_f32_e32 v136, v136
	v_exp_f32_e32 v137, v137
	v_exp_f32_e32 v138, v138
	v_exp_f32_e32 v139, v139
	v_add_f32_e32 v132, 1.0, v132
	v_add_f32_e32 v133, 1.0, v133
	v_add_f32_e32 v134, 1.0, v134
	v_add_f32_e32 v135, 1.0, v135
	v_add_f32_e32 v136, 1.0, v136
	v_add_f32_e32 v137, 1.0, v137
	v_add_f32_e32 v138, 1.0, v138
	v_add_f32_e32 v139, 1.0, v139
	v_rcp_f32_e32 v132, v132
	v_rcp_f32_e32 v133, v133
	v_rcp_f32_e32 v134, v134
	v_rcp_f32_e32 v135, v135
	v_rcp_f32_e32 v136, v136
	v_rcp_f32_e32 v137, v137
	v_rcp_f32_e32 v138, v138
	v_rcp_f32_e32 v139, v139
	v_pk_mul_f32 v[132:133], v[120:121], v[132:133]
	v_pk_mul_f32 v[134:135], v[122:123], v[134:135]
	v_pk_mul_f32 v[136:137], v[116:117], v[136:137]
	v_pk_mul_f32 v[138:139], v[118:119], v[138:139]
	v_cvt_pk_bf16_f32 v244, v132, v133
	v_cvt_pk_bf16_f32 v245, v134, v135
	v_cvt_pk_bf16_f32 v246, v136, v137
	v_cvt_pk_bf16_f32 v247, v138, v139
	s_mov_b64 s[8:9], 0x10000
	v_lshl_add_u64 v[156:157], v[154:155], 0, s[8:9]
	global_store_dwordx4 v[156:157], v[244:247], off offset:0
	s_waitcnt vmcnt(10)
	v_lshlrev_b32_e32 v132, 16, v186
	v_and_b32_e32 v133, 0xffff0000, v186
	v_lshlrev_b32_e32 v134, 16, v187
	v_and_b32_e32 v135, 0xffff0000, v187
	v_lshlrev_b32_e32 v136, 16, v188
	v_and_b32_e32 v137, 0xffff0000, v188
	v_lshlrev_b32_e32 v138, 16, v189
	v_and_b32_e32 v139, 0xffff0000, v189
	s_mov_b64 s[8:9], 0x4c8000
	v_lshl_add_u64 v[156:157], v[152:153], 0, s[8:9]
	global_load_dwordx4 v[186:189], v[156:157], off offset:-3840
	v_med3_f32 v132, v132, s97, v226
	v_med3_f32 v133, v133, s97, v226
	v_med3_f32 v134, v134, s97, v226
	v_med3_f32 v135, v135, s97, v226
	v_med3_f32 v136, v136, s97, v226
	v_med3_f32 v137, v137, s97, v226
	v_med3_f32 v138, v138, s97, v226
	v_med3_f32 v139, v139, s97, v226
	v_mul_f32_e32 v132, 0xbfb8aa3b, v132
	v_mul_f32_e32 v133, 0xbfb8aa3b, v133
	v_mul_f32_e32 v134, 0xbfb8aa3b, v134
	v_mul_f32_e32 v135, 0xbfb8aa3b, v135
	v_mul_f32_e32 v136, 0xbfb8aa3b, v136
	v_mul_f32_e32 v137, 0xbfb8aa3b, v137
	v_mul_f32_e32 v138, 0xbfb8aa3b, v138
	v_mul_f32_e32 v139, 0xbfb8aa3b, v139
	v_exp_f32_e32 v132, v132
	v_exp_f32_e32 v133, v133
	v_exp_f32_e32 v134, v134
	v_exp_f32_e32 v135, v135
	v_exp_f32_e32 v136, v136
	v_exp_f32_e32 v137, v137
	v_exp_f32_e32 v138, v138
	v_exp_f32_e32 v139, v139
	v_add_f32_e32 v132, 1.0, v132
	v_add_f32_e32 v133, 1.0, v133
	v_add_f32_e32 v134, 1.0, v134
	v_add_f32_e32 v135, 1.0, v135
	v_add_f32_e32 v136, 1.0, v136
	v_add_f32_e32 v137, 1.0, v137
	v_add_f32_e32 v138, 1.0, v138
	v_add_f32_e32 v139, 1.0, v139
	v_rcp_f32_e32 v132, v132
	v_rcp_f32_e32 v133, v133
	v_rcp_f32_e32 v134, v134
	v_rcp_f32_e32 v135, v135
	v_rcp_f32_e32 v136, v136
	v_rcp_f32_e32 v137, v137
	v_rcp_f32_e32 v138, v138
	v_rcp_f32_e32 v139, v139
	v_pk_mul_f32 v[132:133], v[88:89], v[132:133]
	v_pk_mul_f32 v[134:135], v[90:91], v[134:135]
	v_pk_mul_f32 v[136:137], v[84:85], v[136:137]
	v_pk_mul_f32 v[138:139], v[86:87], v[138:139]
	v_cvt_pk_bf16_f32 v248, v132, v133
	v_cvt_pk_bf16_f32 v249, v134, v135
	v_cvt_pk_bf16_f32 v250, v136, v137
	v_cvt_pk_bf16_f32 v251, v138, v139
	s_mov_b64 s[8:9], 0x10000
	v_lshl_add_u64 v[156:157], v[154:155], 0, s[8:9]
	global_store_dwordx4 v[156:157], v[248:251], off offset:256
	s_waitcnt vmcnt(11)
; __device__ __forceinline__ unsigned pk2(float lo, float hi) { f32x2_t v = {lo, hi}; bf16x2_t b = __builtin_convertvector(v, bf16x2_t); return __builtin_bit_cast(unsigned, b); }
;     static __device__ __forceinline__ float e1(float x) { return 1.0f + __expf(-fminf(fmaxf(x, -60.f), 60.f)); }
;     __device__ __forceinline__ void operator()(f32x4 (&acc)[2][2][4][2], const Unit& u, int wr, int wc, int fr, int fq) const {
;         const int row0 = u.pm * BM + wr * 64 + fr, col0 = u.pn * BM + wc * 32 + 8 * fq;
; #pragma unroll
;         for (int ai = 0; ai < 2; ++ai)
; #pragma unroll
;             for (int m = 0; m < 4; ++m) {
;                 const int row = row0 + ai * HALF + m * 16;
; #pragma unroll
;                 for (int bj = 0; bj < 2; ++bj) {
;                     const int col = col0 + bj * HALF;
;                     const bf16_t* gp = proj + (size_t)row * NP + C_GATE + u.z * D + col;
;                     const u32x4 ga = *(const u32x4*)gp;
;                     float sc[8];
;                     { float a[8]; unpack8(ga, a);
; #pragma unroll
;                       for (int j = 0; j < 8; ++j) sc[j] = __builtin_amdgcn_rcpf(e1(a[j])); }
;                     if (u.z < 2) { const u32x4 gb = *(const u32x4*)(gp + D); float b[8]; unpack8(gb, b);
; #pragma unroll
;                       for (int j = 0; j < 8; ++j) sc[j] *= e1(b[j]); }
;                     f32x4 v0 = acc[ai][bj][m][0], v1 = acc[ai][bj][m][1];
;                     v0[0] *= sc[0]; v0[1] *= sc[1]; v0[2] *= sc[2]; v0[3] *= sc[3]; v1[0] *= sc[4]; v1[1] *= sc[5]; v1[2] *= sc[6]; v1[3] *= sc[7];
;                     if (u.z < 2) { acc[ai][bj][m][0] = v0; acc[ai][bj][m][1] = v1; }
;                     else { u32x4 w; w.x = pk2(v0[0], v0[1]); w.y = pk2(v0[2], v0[3]); w.z = pk2(v1[0], v1[1]); w.w = pk2(v1[2], v1[3]); *(u32x4*)(YB + (size_t)row * D + col) = w; }
	v_lshlrev_b32_e32 v132, 16, v194
	v_and_b32_e32 v133, 0xffff0000, v194
	v_lshlrev_b32_e32 v134, 16, v195
	v_and_b32_e32 v135, 0xffff0000, v195
	v_lshlrev_b32_e32 v136, 16, v196
	v_and_b32_e32 v137, 0xffff0000, v196
	v_lshlrev_b32_e32 v138, 16, v197
	v_and_b32_e32 v139, 0xffff0000, v197
	s_mov_b64 s[8:9], 0x550000
	v_lshl_add_u64 v[156:157], v[152:153], 0, s[8:9]
	global_load_dwordx4 v[194:197], v[156:157], off offset:-4096
	v_med3_f32 v132, v132, s97, v226
	v_med3_f32 v133, v133, s97, v226
	v_med3_f32 v134, v134, s97, v226
	v_med3_f32 v135, v135, s97, v226
	v_med3_f32 v136, v136, s97, v226
	v_med3_f32 v137, v137, s97, v226
	v_med3_f32 v138, v138, s97, v226
	v_med3_f32 v139, v139, s97, v226
	v_mul_f32_e32 v132, 0xbfb8aa3b, v132
	v_mul_f32_e32 v133, 0xbfb8aa3b, v133
	v_mul_f32_e32 v134, 0xbfb8aa3b, v134
	v_mul_f32_e32 v135, 0xbfb8aa3b, v135
	v_mul_f32_e32 v136, 0xbfb8aa3b, v136
	v_mul_f32_e32 v137, 0xbfb8aa3b, v137
	v_mul_f32_e32 v138, 0xbfb8aa3b, v138
	v_mul_f32_e32 v139, 0xbfb8aa3b, v139
	v_exp_f32_e32 v132, v132
	v_exp_f32_e32 v133, v133
	v_exp_f32_e32 v134, v134
	v_exp_f32_e32 v135, v135
	v_exp_f32_e32 v136, v136
	v_exp_f32_e32 v137, v137
	v_exp_f32_e32 v138, v138
	v_exp_f32_e32 v139, v139
	v_add_f32_e32 v132, 1.0, v132
	v_add_f32_e32 v133, 1.0, v133
	v_add_f32_e32 v134, 1.0, v134
	v_add_f32_e32 v135, 1.0, v135
	v_add_f32_e32 v136, 1.0, v136
	v_add_f32_e32 v137, 1.0, v137
	v_add_f32_e32 v138, 1.0, v138
	v_add_f32_e32 v139, 1.0, v139
	v_rcp_f32_e32 v132, v132
	v_rcp_f32_e32 v133, v133
	v_rcp_f32_e32 v134, v134
	v_rcp_f32_e32 v135, v135
	v_rcp_f32_e32 v136, v136
	v_rcp_f32_e32 v137, v137
	v_rcp_f32_e32 v138, v138
	v_rcp_f32_e32 v139, v139
	v_pk_mul_f32 v[132:133], v[112:113], v[132:133]
	v_pk_mul_f32 v[134:135], v[114:115], v[134:135]
	v_pk_mul_f32 v[136:137], v[108:109], v[136:137]
	v_pk_mul_f32 v[138:139], v[110:111], v[138:139]
	v_cvt_pk_bf16_f32 v244, v132, v133
	v_cvt_pk_bf16_f32 v245, v134, v135
	v_cvt_pk_bf16_f32 v246, v136, v137
	v_cvt_pk_bf16_f32 v247, v138, v139
	s_mov_b64 s[8:9], 0x20000
	v_lshl_add_u64 v[156:157], v[154:155], 0, s[8:9]
	global_store_dwordx4 v[156:157], v[244:247], off offset:0
	s_waitcnt vmcnt(12)
	v_lshlrev_b32_e32 v132, 16, v206
	v_and_b32_e32 v133, 0xffff0000, v206
	v_lshlrev_b32_e32 v134, 16, v207
	v_and_b32_e32 v135, 0xffff0000, v207
	v_lshlrev_b32_e32 v136, 16, v208
	v_and_b32_e32 v137, 0xffff0000, v208
	v_lshlrev_b32_e32 v138, 16, v209
	v_and_b32_e32 v139, 0xffff0000, v209
	s_mov_b64 s[8:9], 0x550000
	v_lshl_add_u64 v[156:157], v[152:153], 0, s[8:9]
	global_load_dwordx4 v[206:209], v[156:157], off offset:-3840
	v_med3_f32 v132, v132, s97, v226
	v_med3_f32 v133, v133, s97, v226
	v_med3_f32 v134, v134, s97, v226
	v_med3_f32 v135, v135, s97, v226
	v_med3_f32 v136, v136, s97, v226
	v_med3_f32 v137, v137, s97, v226
	v_med3_f32 v138, v138, s97, v226
	v_med3_f32 v139, v139, s97, v226
	v_mul_f32_e32 v132, 0xbfb8aa3b, v132
	v_mul_f32_e32 v133, 0xbfb8aa3b, v133
	v_mul_f32_e32 v134, 0xbfb8aa3b, v134
	v_mul_f32_e32 v135, 0xbfb8aa3b, v135
	v_mul_f32_e32 v136, 0xbfb8aa3b, v136
	v_mul_f32_e32 v137, 0xbfb8aa3b, v137
	v_mul_f32_e32 v138, 0xbfb8aa3b, v138
	v_mul_f32_e32 v139, 0xbfb8aa3b, v139
	v_exp_f32_e32 v132, v132
	v_exp_f32_e32 v133, v133
	v_exp_f32_e32 v134, v134
	v_exp_f32_e32 v135, v135
	v_exp_f32_e32 v136, v136
	v_exp_f32_e32 v137, v137
	v_exp_f32_e32 v138, v138
	v_exp_f32_e32 v139, v139
	v_add_f32_e32 v132, 1.0, v132
	v_add_f32_e32 v133, 1.0, v133
	v_add_f32_e32 v134, 1.0, v134
	v_add_f32_e32 v135, 1.0, v135
	v_add_f32_e32 v136, 1.0, v136
	v_add_f32_e32 v137, 1.0, v137
	v_add_f32_e32 v138, 1.0, v138
	v_add_f32_e32 v139, 1.0, v139
	v_rcp_f32_e32 v132, v132
	v_rcp_f32_e32 v133, v133
	v_rcp_f32_e32 v134, v134
	v_rcp_f32_e32 v135, v135
	v_rcp_f32_e32 v136, v136
	v_rcp_f32_e32 v137, v137
	v_rcp_f32_e32 v138, v138
	v_rcp_f32_e32 v139, v139
	v_pk_mul_f32 v[132:133], v[80:81], v[132:133]
	v_pk_mul_f32 v[134:135], v[82:83], v[134:135]
	v_pk_mul_f32 v[136:137], v[76:77], v[136:137]
	v_pk_mul_f32 v[138:139], v[78:79], v[138:139]
	v_cvt_pk_bf16_f32 v248, v132, v133
	v_cvt_pk_bf16_f32 v249, v134, v135
	v_cvt_pk_bf16_f32 v250, v136, v137
	v_cvt_pk_bf16_f32 v251, v138, v139
	s_mov_b64 s[8:9], 0x20000
	v_lshl_add_u64 v[156:157], v[154:155], 0, s[8:9]
	global_store_dwordx4 v[156:157], v[248:251], off offset:256
	s_waitcnt vmcnt(13)
	v_lshlrev_b32_e32 v132, 16, v228
	v_and_b32_e32 v133, 0xffff0000, v228
	v_lshlrev_b32_e32 v134, 16, v229
	v_and_b32_e32 v135, 0xffff0000, v229
	v_lshlrev_b32_e32 v136, 16, v230
	v_and_b32_e32 v137, 0xffff0000, v230
	v_lshlrev_b32_e32 v138, 16, v231
	v_and_b32_e32 v139, 0xffff0000, v231
	s_mov_b64 s[8:9], 0x5d8000
	v_lshl_add_u64 v[156:157], v[152:153], 0, s[8:9]
	global_load_dwordx4 v[228:231], v[156:157], off offset:-4096
	v_med3_f32 v132, v132, s97, v226
	v_med3_f32 v133, v133, s97, v226
	v_med3_f32 v134, v134, s97, v226
	v_med3_f32 v135, v135, s97, v226
	v_med3_f32 v136, v136, s97, v226
	v_med3_f32 v137, v137, s97, v226
	v_med3_f32 v138, v138, s97, v226
	v_med3_f32 v139, v139, s97, v226
	v_mul_f32_e32 v132, 0xbfb8aa3b, v132
	v_mul_f32_e32 v133, 0xbfb8aa3b, v133
	v_mul_f32_e32 v134, 0xbfb8aa3b, v134
	v_mul_f32_e32 v135, 0xbfb8aa3b, v135
	v_mul_f32_e32 v136, 0xbfb8aa3b, v136
	v_mul_f32_e32 v137, 0xbfb8aa3b, v137
	v_mul_f32_e32 v138, 0xbfb8aa3b, v138
	v_mul_f32_e32 v139, 0xbfb8aa3b, v139
	v_exp_f32_e32 v132, v132
	v_exp_f32_e32 v133, v133
	v_exp_f32_e32 v134, v134
	v_exp_f32_e32 v135, v135
	v_exp_f32_e32 v136, v136
	v_exp_f32_e32 v137, v137
	v_exp_f32_e32 v138, v138
	v_exp_f32_e32 v139, v139
	v_add_f32_e32 v132, 1.0, v132
	v_add_f32_e32 v133, 1.0, v133
	v_add_f32_e32 v134, 1.0, v134
	v_add_f32_e32 v135, 1.0, v135
	v_add_f32_e32 v136, 1.0, v136
	v_add_f32_e32 v137, 1.0, v137
	v_add_f32_e32 v138, 1.0, v138
	v_add_f32_e32 v139, 1.0, v139
	v_rcp_f32_e32 v132, v132
	v_rcp_f32_e32 v133, v133
	v_rcp_f32_e32 v134, v134
	v_rcp_f32_e32 v135, v135
	v_rcp_f32_e32 v136, v136
	v_rcp_f32_e32 v137, v137
	v_rcp_f32_e32 v138, v138
	v_rcp_f32_e32 v139, v139
	v_pk_mul_f32 v[132:133], v[104:105], v[132:133]
	v_pk_mul_f32 v[134:135], v[106:107], v[134:135]
	v_pk_mul_f32 v[136:137], v[100:101], v[136:137]
	v_pk_mul_f32 v[138:139], v[102:103], v[138:139]
	v_cvt_pk_bf16_f32 v244, v132, v133
	v_cvt_pk_bf16_f32 v245, v134, v135
	v_cvt_pk_bf16_f32 v246, v136, v137
	v_cvt_pk_bf16_f32 v247, v138, v139
	s_mov_b64 s[8:9], 0x30000
	v_lshl_add_u64 v[156:157], v[154:155], 0, s[8:9]
	global_store_dwordx4 v[156:157], v[244:247], off offset:0
	s_waitcnt vmcnt(14)
; __device__ __forceinline__ unsigned pk2(float lo, float hi) { f32x2_t v = {lo, hi}; bf16x2_t b = __builtin_convertvector(v, bf16x2_t); return __builtin_bit_cast(unsigned, b); }
;     static __device__ __forceinline__ float e1(float x) { return 1.0f + __expf(-fminf(fmaxf(x, -60.f), 60.f)); }
;     __device__ __forceinline__ void operator()(f32x4 (&acc)[2][2][4][2], const Unit& u, int wr, int wc, int fr, int fq) const {
;         const int row0 = u.pm * BM + wr * 64 + fr, col0 = u.pn * BM + wc * 32 + 8 * fq;
; #pragma unroll
;         for (int ai = 0; ai < 2; ++ai)
; #pragma unroll
;             for (int m = 0; m < 4; ++m) {
;                 const int row = row0 + ai * HALF + m * 16;
; #pragma unroll
;                 for (int bj = 0; bj < 2; ++bj) {
;                     const int col = col0 + bj * HALF;
;                     const bf16_t* gp = proj + (size_t)row * NP + C_GATE + u.z * D + col;
;                     const u32x4 ga = *(const u32x4*)gp;
;                     float sc[8];
;                     { float a[8]; unpack8(ga, a);
; #pragma unroll
;                       for (int j = 0; j < 8; ++j) sc[j] = __builtin_amdgcn_rcpf(e1(a[j])); }
;                     if (u.z < 2) { const u32x4 gb = *(const u32x4*)(gp + D); float b[8]; unpack8(gb, b);
; #pragma unroll
;                       for (int j = 0; j < 8; ++j) sc[j] *= e1(b[j]); }
;                     f32x4 v0 = acc[ai][bj][m][0], v1 = acc[ai][bj][m][1];
;                     v0[0] *= sc[0]; v0[1] *= sc[1]; v0[2] *= sc[2]; v0[3] *= sc[3]; v1[0] *= sc[4]; v1[1] *= sc[5]; v1[2] *= sc[6]; v1[3] *= sc[7];
;                     if (u.z < 2) { acc[ai][bj][m][0] = v0; acc[ai][bj][m][1] = v1; }
;                     else { u32x4 w; w.x = pk2(v0[0], v0[1]); w.y = pk2(v0[2], v0[3]); w.z = pk2(v1[0], v1[1]); w.w = pk2(v1[2], v1[3]); *(u32x4*)(YB + (size_t)row * D + col) = w; }
	v_lshlrev_b32_e32 v132, 16, v236
	v_and_b32_e32 v133, 0xffff0000, v236
	v_lshlrev_b32_e32 v134, 16, v237
	v_and_b32_e32 v135, 0xffff0000, v237
	v_lshlrev_b32_e32 v136, 16, v238
	v_and_b32_e32 v137, 0xffff0000, v238
	v_lshlrev_b32_e32 v138, 16, v239
	v_and_b32_e32 v139, 0xffff0000, v239
	s_mov_b64 s[8:9], 0x5d8000
	v_lshl_add_u64 v[156:157], v[152:153], 0, s[8:9]
	global_load_dwordx4 v[236:239], v[156:157], off offset:-3840
	v_med3_f32 v132, v132, s97, v226
	v_med3_f32 v133, v133, s97, v226
	v_med3_f32 v134, v134, s97, v226
	v_med3_f32 v135, v135, s97, v226
	v_med3_f32 v136, v136, s97, v226
	v_med3_f32 v137, v137, s97, v226
	v_med3_f32 v138, v138, s97, v226
	v_med3_f32 v139, v139, s97, v226
	v_mul_f32_e32 v132, 0xbfb8aa3b, v132
	v_mul_f32_e32 v133, 0xbfb8aa3b, v133
	v_mul_f32_e32 v134, 0xbfb8aa3b, v134
	v_mul_f32_e32 v135, 0xbfb8aa3b, v135
	v_mul_f32_e32 v136, 0xbfb8aa3b, v136
	v_mul_f32_e32 v137, 0xbfb8aa3b, v137
	v_mul_f32_e32 v138, 0xbfb8aa3b, v138
	v_mul_f32_e32 v139, 0xbfb8aa3b, v139
	v_exp_f32_e32 v132, v132
	v_exp_f32_e32 v133, v133
	v_exp_f32_e32 v134, v134
	v_exp_f32_e32 v135, v135
	v_exp_f32_e32 v136, v136
	v_exp_f32_e32 v137, v137
	v_exp_f32_e32 v138, v138
	v_exp_f32_e32 v139, v139
	v_add_f32_e32 v132, 1.0, v132
	v_add_f32_e32 v133, 1.0, v133
	v_add_f32_e32 v134, 1.0, v134
	v_add_f32_e32 v135, 1.0, v135
	v_add_f32_e32 v136, 1.0, v136
	v_add_f32_e32 v137, 1.0, v137
	v_add_f32_e32 v138, 1.0, v138
	v_add_f32_e32 v139, 1.0, v139
	v_rcp_f32_e32 v132, v132
	v_rcp_f32_e32 v133, v133
	v_rcp_f32_e32 v134, v134
	v_rcp_f32_e32 v135, v135
	v_rcp_f32_e32 v136, v136
	v_rcp_f32_e32 v137, v137
	v_rcp_f32_e32 v138, v138
	v_rcp_f32_e32 v139, v139
	v_pk_mul_f32 v[132:133], v[72:73], v[132:133]
	v_pk_mul_f32 v[134:135], v[74:75], v[134:135]
	v_pk_mul_f32 v[136:137], v[68:69], v[136:137]
	v_pk_mul_f32 v[138:139], v[70:71], v[138:139]
	v_cvt_pk_bf16_f32 v248, v132, v133
	v_cvt_pk_bf16_f32 v249, v134, v135
	v_cvt_pk_bf16_f32 v250, v136, v137
	v_cvt_pk_bf16_f32 v251, v138, v139
	s_mov_b64 s[8:9], 0x30000
	v_lshl_add_u64 v[156:157], v[154:155], 0, s[8:9]
	global_store_dwordx4 v[156:157], v[248:251], off offset:256
	s_waitcnt vmcnt(15)
	v_lshlrev_b32_e32 v132, 16, v162
	v_and_b32_e32 v133, 0xffff0000, v162
	v_lshlrev_b32_e32 v134, 16, v163
	v_and_b32_e32 v135, 0xffff0000, v163
	v_lshlrev_b32_e32 v136, 16, v164
	v_and_b32_e32 v137, 0xffff0000, v164
	v_lshlrev_b32_e32 v138, 16, v165
	v_and_b32_e32 v139, 0xffff0000, v165
	v_med3_f32 v132, v132, s97, v226
	v_med3_f32 v133, v133, s97, v226
	v_med3_f32 v134, v134, s97, v226
	v_med3_f32 v135, v135, s97, v226
	v_med3_f32 v136, v136, s97, v226
	v_med3_f32 v137, v137, s97, v226
	v_med3_f32 v138, v138, s97, v226
	v_med3_f32 v139, v139, s97, v226
	v_mul_f32_e32 v132, 0xbfb8aa3b, v132
	v_mul_f32_e32 v133, 0xbfb8aa3b, v133
	v_mul_f32_e32 v134, 0xbfb8aa3b, v134
	v_mul_f32_e32 v135, 0xbfb8aa3b, v135
	v_mul_f32_e32 v136, 0xbfb8aa3b, v136
	v_mul_f32_e32 v137, 0xbfb8aa3b, v137
	v_mul_f32_e32 v138, 0xbfb8aa3b, v138
	v_mul_f32_e32 v139, 0xbfb8aa3b, v139
	v_exp_f32_e32 v132, v132
	v_exp_f32_e32 v133, v133
	v_exp_f32_e32 v134, v134
	v_exp_f32_e32 v135, v135
	v_exp_f32_e32 v136, v136
	v_exp_f32_e32 v137, v137
	v_exp_f32_e32 v138, v138
	v_exp_f32_e32 v139, v139
	v_add_f32_e32 v132, 1.0, v132
	v_add_f32_e32 v133, 1.0, v133
	v_add_f32_e32 v134, 1.0, v134
	v_add_f32_e32 v135, 1.0, v135
	v_add_f32_e32 v136, 1.0, v136
	v_add_f32_e32 v137, 1.0, v137
	v_add_f32_e32 v138, 1.0, v138
	v_add_f32_e32 v139, 1.0, v139
	v_rcp_f32_e32 v132, v132
	v_rcp_f32_e32 v133, v133
	v_rcp_f32_e32 v134, v134
	v_rcp_f32_e32 v135, v135
	v_rcp_f32_e32 v136, v136
	v_rcp_f32_e32 v137, v137
	v_rcp_f32_e32 v138, v138
	v_rcp_f32_e32 v139, v139
	v_pk_mul_f32 v[132:133], v[64:65], v[132:133]
	v_pk_mul_f32 v[134:135], v[66:67], v[134:135]
	v_pk_mul_f32 v[136:137], v[60:61], v[136:137]
	v_pk_mul_f32 v[138:139], v[62:63], v[138:139]
	v_cvt_pk_bf16_f32 v244, v132, v133
	v_cvt_pk_bf16_f32 v245, v134, v135
	v_cvt_pk_bf16_f32 v246, v136, v137
	v_cvt_pk_bf16_f32 v247, v138, v139
	s_mov_b64 s[8:9], 0x80000
	v_lshl_add_u64 v[156:157], v[154:155], 0, s[8:9]
	global_store_dwordx4 v[156:157], v[244:247], off offset:0
	s_waitcnt vmcnt(14)
	v_lshlrev_b32_e32 v132, 16, v170
	v_and_b32_e32 v133, 0xffff0000, v170
	v_lshlrev_b32_e32 v134, 16, v171
	v_and_b32_e32 v135, 0xffff0000, v171
	v_lshlrev_b32_e32 v136, 16, v172
	v_and_b32_e32 v137, 0xffff0000, v172
	v_lshlrev_b32_e32 v138, 16, v173
	v_and_b32_e32 v139, 0xffff0000, v173
	v_med3_f32 v132, v132, s97, v226
	v_med3_f32 v133, v133, s97, v226
	v_med3_f32 v134, v134, s97, v226
	v_med3_f32 v135, v135, s97, v226
	v_med3_f32 v136, v136, s97, v226
	v_med3_f32 v137, v137, s97, v226
	v_med3_f32 v138, v138, s97, v226
	v_med3_f32 v139, v139, s97, v226
	v_mul_f32_e32 v132, 0xbfb8aa3b, v132
	v_mul_f32_e32 v133, 0xbfb8aa3b, v133
	v_mul_f32_e32 v134, 0xbfb8aa3b, v134
	v_mul_f32_e32 v135, 0xbfb8aa3b, v135
	v_mul_f32_e32 v136, 0xbfb8aa3b, v136
	v_mul_f32_e32 v137, 0xbfb8aa3b, v137
	v_mul_f32_e32 v138, 0xbfb8aa3b, v138
	v_mul_f32_e32 v139, 0xbfb8aa3b, v139
	v_exp_f32_e32 v132, v132
	v_exp_f32_e32 v133, v133
	v_exp_f32_e32 v134, v134
	v_exp_f32_e32 v135, v135
	v_exp_f32_e32 v136, v136
	v_exp_f32_e32 v137, v137
	v_exp_f32_e32 v138, v138
	v_exp_f32_e32 v139, v139
	v_add_f32_e32 v132, 1.0, v132
	v_add_f32_e32 v133, 1.0, v133
	v_add_f32_e32 v134, 1.0, v134
	v_add_f32_e32 v135, 1.0, v135
	v_add_f32_e32 v136, 1.0, v136
	v_add_f32_e32 v137, 1.0, v137
	v_add_f32_e32 v138, 1.0, v138
	v_add_f32_e32 v139, 1.0, v139
	v_rcp_f32_e32 v132, v132
	v_rcp_f32_e32 v133, v133
	v_rcp_f32_e32 v134, v134
	v_rcp_f32_e32 v135, v135
	v_rcp_f32_e32 v136, v136
	v_rcp_f32_e32 v137, v137
	v_rcp_f32_e32 v138, v138
	v_rcp_f32_e32 v139, v139
	v_pk_mul_f32 v[132:133], v[32:33], v[132:133]
	v_pk_mul_f32 v[134:135], v[34:35], v[134:135]
	v_pk_mul_f32 v[136:137], v[28:29], v[136:137]
	v_pk_mul_f32 v[138:139], v[30:31], v[138:139]
	v_cvt_pk_bf16_f32 v248, v132, v133
	v_cvt_pk_bf16_f32 v249, v134, v135
	v_cvt_pk_bf16_f32 v250, v136, v137
	v_cvt_pk_bf16_f32 v251, v138, v139
	s_mov_b64 s[8:9], 0x80000
	v_lshl_add_u64 v[156:157], v[154:155], 0, s[8:9]
	global_store_dwordx4 v[156:157], v[248:251], off offset:256
	s_waitcnt vmcnt(13)
; __device__ __forceinline__ unsigned pk2(float lo, float hi) { f32x2_t v = {lo, hi}; bf16x2_t b = __builtin_convertvector(v, bf16x2_t); return __builtin_bit_cast(unsigned, b); }
;     static __device__ __forceinline__ float e1(float x) { return 1.0f + __expf(-fminf(fmaxf(x, -60.f), 60.f)); }
;     __device__ __forceinline__ void operator()(f32x4 (&acc)[2][2][4][2], const Unit& u, int wr, int wc, int fr, int fq) const {
;         const int row0 = u.pm * BM + wr * 64 + fr, col0 = u.pn * BM + wc * 32 + 8 * fq;
; #pragma unroll
;         for (int ai = 0; ai < 2; ++ai)
; #pragma unroll
;             for (int m = 0; m < 4; ++m) {
;                 const int row = row0 + ai * HALF + m * 16;
; #pragma unroll
;                 for (int bj = 0; bj < 2; ++bj) {
;                     const int col = col0 + bj * HALF;
;                     const bf16_t* gp = proj + (size_t)row * NP + C_GATE + u.z * D + col;
;                     const u32x4 ga = *(const u32x4*)gp;
;                     float sc[8];
;                     { float a[8]; unpack8(ga, a);
; #pragma unroll
;                       for (int j = 0; j < 8; ++j) sc[j] = __builtin_amdgcn_rcpf(e1(a[j])); }
;                     if (u.z < 2) { const u32x4 gb = *(const u32x4*)(gp + D); float b[8]; unpack8(gb, b);
; #pragma unroll
;                       for (int j = 0; j < 8; ++j) sc[j] *= e1(b[j]); }
;                     f32x4 v0 = acc[ai][bj][m][0], v1 = acc[ai][bj][m][1];
;                     v0[0] *= sc[0]; v0[1] *= sc[1]; v0[2] *= sc[2]; v0[3] *= sc[3]; v1[0] *= sc[4]; v1[1] *= sc[5]; v1[2] *= sc[6]; v1[3] *= sc[7];
;                     if (u.z < 2) { acc[ai][bj][m][0] = v0; acc[ai][bj][m][1] = v1; }
;                     else { u32x4 w; w.x = pk2(v0[0], v0[1]); w.y = pk2(v0[2], v0[3]); w.z = pk2(v1[0], v1[1]); w.w = pk2(v1[2], v1[3]); *(u32x4*)(YB + (size_t)row * D + col) = w; }
	v_lshlrev_b32_e32 v132, 16, v178
	v_and_b32_e32 v133, 0xffff0000, v178
	v_lshlrev_b32_e32 v134, 16, v179
	v_and_b32_e32 v135, 0xffff0000, v179
	v_lshlrev_b32_e32 v136, 16, v180
	v_and_b32_e32 v137, 0xffff0000, v180
	v_lshlrev_b32_e32 v138, 16, v181
	v_and_b32_e32 v139, 0xffff0000, v181
	v_med3_f32 v132, v132, s97, v226
	v_med3_f32 v133, v133, s97, v226
	v_med3_f32 v134, v134, s97, v226
	v_med3_f32 v135, v135, s97, v226
	v_med3_f32 v136, v136, s97, v226
	v_med3_f32 v137, v137, s97, v226
	v_med3_f32 v138, v138, s97, v226
	v_med3_f32 v139, v139, s97, v226
	v_mul_f32_e32 v132, 0xbfb8aa3b, v132
	v_mul_f32_e32 v133, 0xbfb8aa3b, v133
	v_mul_f32_e32 v134, 0xbfb8aa3b, v134
	v_mul_f32_e32 v135, 0xbfb8aa3b, v135
	v_mul_f32_e32 v136, 0xbfb8aa3b, v136
	v_mul_f32_e32 v137, 0xbfb8aa3b, v137
	v_mul_f32_e32 v138, 0xbfb8aa3b, v138
	v_mul_f32_e32 v139, 0xbfb8aa3b, v139
	v_exp_f32_e32 v132, v132
	v_exp_f32_e32 v133, v133
	v_exp_f32_e32 v134, v134
	v_exp_f32_e32 v135, v135
	v_exp_f32_e32 v136, v136
	v_exp_f32_e32 v137, v137
	v_exp_f32_e32 v138, v138
	v_exp_f32_e32 v139, v139
	v_add_f32_e32 v132, 1.0, v132
	v_add_f32_e32 v133, 1.0, v133
	v_add_f32_e32 v134, 1.0, v134
	v_add_f32_e32 v135, 1.0, v135
	v_add_f32_e32 v136, 1.0, v136
	v_add_f32_e32 v137, 1.0, v137
	v_add_f32_e32 v138, 1.0, v138
	v_add_f32_e32 v139, 1.0, v139
	v_rcp_f32_e32 v132, v132
	v_rcp_f32_e32 v133, v133
	v_rcp_f32_e32 v134, v134
	v_rcp_f32_e32 v135, v135
	v_rcp_f32_e32 v136, v136
	v_rcp_f32_e32 v137, v137
	v_rcp_f32_e32 v138, v138
	v_rcp_f32_e32 v139, v139
	v_pk_mul_f32 v[132:133], v[56:57], v[132:133]
	v_pk_mul_f32 v[134:135], v[58:59], v[134:135]
	v_pk_mul_f32 v[136:137], v[52:53], v[136:137]
	v_pk_mul_f32 v[138:139], v[54:55], v[138:139]
	v_cvt_pk_bf16_f32 v244, v132, v133
	v_cvt_pk_bf16_f32 v245, v134, v135
	v_cvt_pk_bf16_f32 v246, v136, v137
	v_cvt_pk_bf16_f32 v247, v138, v139
	s_mov_b64 s[8:9], 0x90000
	v_lshl_add_u64 v[156:157], v[154:155], 0, s[8:9]
	global_store_dwordx4 v[156:157], v[244:247], off offset:0
	s_waitcnt vmcnt(12)
	v_lshlrev_b32_e32 v132, 16, v186
	v_and_b32_e32 v133, 0xffff0000, v186
	v_lshlrev_b32_e32 v134, 16, v187
	v_and_b32_e32 v135, 0xffff0000, v187
	v_lshlrev_b32_e32 v136, 16, v188
	v_and_b32_e32 v137, 0xffff0000, v188
	v_lshlrev_b32_e32 v138, 16, v189
	v_and_b32_e32 v139, 0xffff0000, v189
	v_med3_f32 v132, v132, s97, v226
	v_med3_f32 v133, v133, s97, v226
	v_med3_f32 v134, v134, s97, v226
	v_med3_f32 v135, v135, s97, v226
	v_med3_f32 v136, v136, s97, v226
	v_med3_f32 v137, v137, s97, v226
	v_med3_f32 v138, v138, s97, v226
	v_med3_f32 v139, v139, s97, v226
	v_mul_f32_e32 v132, 0xbfb8aa3b, v132
	v_mul_f32_e32 v133, 0xbfb8aa3b, v133
	v_mul_f32_e32 v134, 0xbfb8aa3b, v134
	v_mul_f32_e32 v135, 0xbfb8aa3b, v135
	v_mul_f32_e32 v136, 0xbfb8aa3b, v136
	v_mul_f32_e32 v137, 0xbfb8aa3b, v137
	v_mul_f32_e32 v138, 0xbfb8aa3b, v138
	v_mul_f32_e32 v139, 0xbfb8aa3b, v139
	v_exp_f32_e32 v132, v132
	v_exp_f32_e32 v133, v133
	v_exp_f32_e32 v134, v134
	v_exp_f32_e32 v135, v135
	v_exp_f32_e32 v136, v136
	v_exp_f32_e32 v137, v137
	v_exp_f32_e32 v138, v138
	v_exp_f32_e32 v139, v139
	v_add_f32_e32 v132, 1.0, v132
	v_add_f32_e32 v133, 1.0, v133
	v_add_f32_e32 v134, 1.0, v134
	v_add_f32_e32 v135, 1.0, v135
	v_add_f32_e32 v136, 1.0, v136
	v_add_f32_e32 v137, 1.0, v137
	v_add_f32_e32 v138, 1.0, v138
	v_add_f32_e32 v139, 1.0, v139
	v_rcp_f32_e32 v132, v132
	v_rcp_f32_e32 v133, v133
	v_rcp_f32_e32 v134, v134
	v_rcp_f32_e32 v135, v135
	v_rcp_f32_e32 v136, v136
	v_rcp_f32_e32 v137, v137
	v_rcp_f32_e32 v138, v138
	v_rcp_f32_e32 v139, v139
	v_pk_mul_f32 v[132:133], v[24:25], v[132:133]
	v_pk_mul_f32 v[134:135], v[26:27], v[134:135]
	v_pk_mul_f32 v[136:137], v[20:21], v[136:137]
	v_pk_mul_f32 v[138:139], v[22:23], v[138:139]
	v_cvt_pk_bf16_f32 v248, v132, v133
	v_cvt_pk_bf16_f32 v249, v134, v135
	v_cvt_pk_bf16_f32 v250, v136, v137
	v_cvt_pk_bf16_f32 v251, v138, v139
	s_mov_b64 s[8:9], 0x90000
	v_lshl_add_u64 v[156:157], v[154:155], 0, s[8:9]
	global_store_dwordx4 v[156:157], v[248:251], off offset:256
	s_waitcnt vmcnt(11)
	v_lshlrev_b32_e32 v132, 16, v194
	v_and_b32_e32 v133, 0xffff0000, v194
	v_lshlrev_b32_e32 v134, 16, v195
	v_and_b32_e32 v135, 0xffff0000, v195
	v_lshlrev_b32_e32 v136, 16, v196
	v_and_b32_e32 v137, 0xffff0000, v196
	v_lshlrev_b32_e32 v138, 16, v197
	v_and_b32_e32 v139, 0xffff0000, v197
	v_med3_f32 v132, v132, s97, v226
	v_med3_f32 v133, v133, s97, v226
	v_med3_f32 v134, v134, s97, v226
	v_med3_f32 v135, v135, s97, v226
	v_med3_f32 v136, v136, s97, v226
	v_med3_f32 v137, v137, s97, v226
	v_med3_f32 v138, v138, s97, v226
	v_med3_f32 v139, v139, s97, v226
	v_mul_f32_e32 v132, 0xbfb8aa3b, v132
	v_mul_f32_e32 v133, 0xbfb8aa3b, v133
	v_mul_f32_e32 v134, 0xbfb8aa3b, v134
	v_mul_f32_e32 v135, 0xbfb8aa3b, v135
	v_mul_f32_e32 v136, 0xbfb8aa3b, v136
	v_mul_f32_e32 v137, 0xbfb8aa3b, v137
	v_mul_f32_e32 v138, 0xbfb8aa3b, v138
	v_mul_f32_e32 v139, 0xbfb8aa3b, v139
	v_exp_f32_e32 v132, v132
	v_exp_f32_e32 v133, v133
	v_exp_f32_e32 v134, v134
	v_exp_f32_e32 v135, v135
	v_exp_f32_e32 v136, v136
	v_exp_f32_e32 v137, v137
	v_exp_f32_e32 v138, v138
	v_exp_f32_e32 v139, v139
	v_add_f32_e32 v132, 1.0, v132
	v_add_f32_e32 v133, 1.0, v133
	v_add_f32_e32 v134, 1.0, v134
	v_add_f32_e32 v135, 1.0, v135
	v_add_f32_e32 v136, 1.0, v136
	v_add_f32_e32 v137, 1.0, v137
	v_add_f32_e32 v138, 1.0, v138
	v_add_f32_e32 v139, 1.0, v139
	v_rcp_f32_e32 v132, v132
	v_rcp_f32_e32 v133, v133
	v_rcp_f32_e32 v134, v134
	v_rcp_f32_e32 v135, v135
	v_rcp_f32_e32 v136, v136
	v_rcp_f32_e32 v137, v137
	v_rcp_f32_e32 v138, v138
	v_rcp_f32_e32 v139, v139
	v_pk_mul_f32 v[132:133], v[48:49], v[132:133]
	v_pk_mul_f32 v[134:135], v[50:51], v[134:135]
	v_pk_mul_f32 v[136:137], v[44:45], v[136:137]
	v_pk_mul_f32 v[138:139], v[46:47], v[138:139]
	v_cvt_pk_bf16_f32 v244, v132, v133
	v_cvt_pk_bf16_f32 v245, v134, v135
	v_cvt_pk_bf16_f32 v246, v136, v137
	v_cvt_pk_bf16_f32 v247, v138, v139
	s_mov_b64 s[8:9], 0xa0000
	v_lshl_add_u64 v[156:157], v[154:155], 0, s[8:9]
	global_store_dwordx4 v[156:157], v[244:247], off offset:0
	s_waitcnt vmcnt(10)
; __device__ __forceinline__ unsigned pk2(float lo, float hi) { f32x2_t v = {lo, hi}; bf16x2_t b = __builtin_convertvector(v, bf16x2_t); return __builtin_bit_cast(unsigned, b); }
;     static __device__ __forceinline__ float e1(float x) { return 1.0f + __expf(-fminf(fmaxf(x, -60.f), 60.f)); }
;     __device__ __forceinline__ void operator()(f32x4 (&acc)[2][2][4][2], const Unit& u, int wr, int wc, int fr, int fq) const {
;         const int row0 = u.pm * BM + wr * 64 + fr, col0 = u.pn * BM + wc * 32 + 8 * fq;
; #pragma unroll
;         for (int ai = 0; ai < 2; ++ai)
; #pragma unroll
;             for (int m = 0; m < 4; ++m) {
;                 const int row = row0 + ai * HALF + m * 16;
; #pragma unroll
;                 for (int bj = 0; bj < 2; ++bj) {
;                     const int col = col0 + bj * HALF;
;                     const bf16_t* gp = proj + (size_t)row * NP + C_GATE + u.z * D + col;
;                     const u32x4 ga = *(const u32x4*)gp;
;                     float sc[8];
;                     { float a[8]; unpack8(ga, a);
; #pragma unroll
;                       for (int j = 0; j < 8; ++j) sc[j] = __builtin_amdgcn_rcpf(e1(a[j])); }
;                     if (u.z < 2) { const u32x4 gb = *(const u32x4*)(gp + D); float b[8]; unpack8(gb, b);
; #pragma unroll
;                       for (int j = 0; j < 8; ++j) sc[j] *= e1(b[j]); }
;                     f32x4 v0 = acc[ai][bj][m][0], v1 = acc[ai][bj][m][1];
;                     v0[0] *= sc[0]; v0[1] *= sc[1]; v0[2] *= sc[2]; v0[3] *= sc[3]; v1[0] *= sc[4]; v1[1] *= sc[5]; v1[2] *= sc[6]; v1[3] *= sc[7];
;                     if (u.z < 2) { acc[ai][bj][m][0] = v0; acc[ai][bj][m][1] = v1; }
;                     else { u32x4 w; w.x = pk2(v0[0], v0[1]); w.y = pk2(v0[2], v0[3]); w.z = pk2(v1[0], v1[1]); w.w = pk2(v1[2], v1[3]); *(u32x4*)(YB + (size_t)row * D + col) = w; }
	v_lshlrev_b32_e32 v132, 16, v206
	v_and_b32_e32 v133, 0xffff0000, v206
	v_lshlrev_b32_e32 v134, 16, v207
	v_and_b32_e32 v135, 0xffff0000, v207
	v_lshlrev_b32_e32 v136, 16, v208
	v_and_b32_e32 v137, 0xffff0000, v208
	v_lshlrev_b32_e32 v138, 16, v209
	v_and_b32_e32 v139, 0xffff0000, v209
	v_med3_f32 v132, v132, s97, v226
	v_med3_f32 v133, v133, s97, v226
	v_med3_f32 v134, v134, s97, v226
	v_med3_f32 v135, v135, s97, v226
	v_med3_f32 v136, v136, s97, v226
	v_med3_f32 v137, v137, s97, v226
	v_med3_f32 v138, v138, s97, v226
	v_med3_f32 v139, v139, s97, v226
	v_mul_f32_e32 v132, 0xbfb8aa3b, v132
	v_mul_f32_e32 v133, 0xbfb8aa3b, v133
	v_mul_f32_e32 v134, 0xbfb8aa3b, v134
	v_mul_f32_e32 v135, 0xbfb8aa3b, v135
	v_mul_f32_e32 v136, 0xbfb8aa3b, v136
	v_mul_f32_e32 v137, 0xbfb8aa3b, v137
	v_mul_f32_e32 v138, 0xbfb8aa3b, v138
	v_mul_f32_e32 v139, 0xbfb8aa3b, v139
	v_exp_f32_e32 v132, v132
	v_exp_f32_e32 v133, v133
	v_exp_f32_e32 v134, v134
	v_exp_f32_e32 v135, v135
	v_exp_f32_e32 v136, v136
	v_exp_f32_e32 v137, v137
	v_exp_f32_e32 v138, v138
	v_exp_f32_e32 v139, v139
	v_add_f32_e32 v132, 1.0, v132
	v_add_f32_e32 v133, 1.0, v133
	v_add_f32_e32 v134, 1.0, v134
	v_add_f32_e32 v135, 1.0, v135
	v_add_f32_e32 v136, 1.0, v136
	v_add_f32_e32 v137, 1.0, v137
	v_add_f32_e32 v138, 1.0, v138
	v_add_f32_e32 v139, 1.0, v139
	v_rcp_f32_e32 v132, v132
	v_rcp_f32_e32 v133, v133
	v_rcp_f32_e32 v134, v134
	v_rcp_f32_e32 v135, v135
	v_rcp_f32_e32 v136, v136
	v_rcp_f32_e32 v137, v137
	v_rcp_f32_e32 v138, v138
	v_rcp_f32_e32 v139, v139
	v_pk_mul_f32 v[132:133], v[16:17], v[132:133]
	v_pk_mul_f32 v[134:135], v[18:19], v[134:135]
	v_pk_mul_f32 v[136:137], v[12:13], v[136:137]
	v_pk_mul_f32 v[138:139], v[14:15], v[138:139]
	v_cvt_pk_bf16_f32 v248, v132, v133
	v_cvt_pk_bf16_f32 v249, v134, v135
	v_cvt_pk_bf16_f32 v250, v136, v137
	v_cvt_pk_bf16_f32 v251, v138, v139
	s_mov_b64 s[8:9], 0xa0000
	v_lshl_add_u64 v[156:157], v[154:155], 0, s[8:9]
	global_store_dwordx4 v[156:157], v[248:251], off offset:256
	s_waitcnt vmcnt(9)
	v_lshlrev_b32_e32 v132, 16, v228
	v_and_b32_e32 v133, 0xffff0000, v228
	v_lshlrev_b32_e32 v134, 16, v229
	v_and_b32_e32 v135, 0xffff0000, v229
	v_lshlrev_b32_e32 v136, 16, v230
	v_and_b32_e32 v137, 0xffff0000, v230
	v_lshlrev_b32_e32 v138, 16, v231
	v_and_b32_e32 v139, 0xffff0000, v231
	v_med3_f32 v132, v132, s97, v226
	v_med3_f32 v133, v133, s97, v226
	v_med3_f32 v134, v134, s97, v226
	v_med3_f32 v135, v135, s97, v226
	v_med3_f32 v136, v136, s97, v226
	v_med3_f32 v137, v137, s97, v226
	v_med3_f32 v138, v138, s97, v226
	v_med3_f32 v139, v139, s97, v226
	v_mul_f32_e32 v132, 0xbfb8aa3b, v132
	v_mul_f32_e32 v133, 0xbfb8aa3b, v133
	v_mul_f32_e32 v134, 0xbfb8aa3b, v134
	v_mul_f32_e32 v135, 0xbfb8aa3b, v135
	v_mul_f32_e32 v136, 0xbfb8aa3b, v136
	v_mul_f32_e32 v137, 0xbfb8aa3b, v137
	v_mul_f32_e32 v138, 0xbfb8aa3b, v138
	v_mul_f32_e32 v139, 0xbfb8aa3b, v139
	v_exp_f32_e32 v132, v132
	v_exp_f32_e32 v133, v133
	v_exp_f32_e32 v134, v134
	v_exp_f32_e32 v135, v135
	v_exp_f32_e32 v136, v136
	v_exp_f32_e32 v137, v137
	v_exp_f32_e32 v138, v138
	v_exp_f32_e32 v139, v139
	v_add_f32_e32 v132, 1.0, v132
	v_add_f32_e32 v133, 1.0, v133
	v_add_f32_e32 v134, 1.0, v134
	v_add_f32_e32 v135, 1.0, v135
	v_add_f32_e32 v136, 1.0, v136
	v_add_f32_e32 v137, 1.0, v137
	v_add_f32_e32 v138, 1.0, v138
	v_add_f32_e32 v139, 1.0, v139
	v_rcp_f32_e32 v132, v132
	v_rcp_f32_e32 v133, v133
	v_rcp_f32_e32 v134, v134
	v_rcp_f32_e32 v135, v135
	v_rcp_f32_e32 v136, v136
	v_rcp_f32_e32 v137, v137
	v_rcp_f32_e32 v138, v138
	v_rcp_f32_e32 v139, v139
	v_pk_mul_f32 v[132:133], v[40:41], v[132:133]
	v_pk_mul_f32 v[134:135], v[42:43], v[134:135]
	v_pk_mul_f32 v[136:137], v[36:37], v[136:137]
	v_pk_mul_f32 v[138:139], v[38:39], v[138:139]
	v_cvt_pk_bf16_f32 v244, v132, v133
	v_cvt_pk_bf16_f32 v245, v134, v135
	v_cvt_pk_bf16_f32 v246, v136, v137
	v_cvt_pk_bf16_f32 v247, v138, v139
	s_mov_b64 s[8:9], 0xb0000
	v_lshl_add_u64 v[156:157], v[154:155], 0, s[8:9]
	global_store_dwordx4 v[156:157], v[244:247], off offset:0
	s_waitcnt vmcnt(8)
	v_lshlrev_b32_e32 v132, 16, v236
	v_and_b32_e32 v133, 0xffff0000, v236
	v_lshlrev_b32_e32 v134, 16, v237
	v_and_b32_e32 v135, 0xffff0000, v237
	v_lshlrev_b32_e32 v136, 16, v238
	v_and_b32_e32 v137, 0xffff0000, v238
	v_lshlrev_b32_e32 v138, 16, v239
	v_and_b32_e32 v139, 0xffff0000, v239
	v_med3_f32 v132, v132, s97, v226
	v_med3_f32 v133, v133, s97, v226
	v_med3_f32 v134, v134, s97, v226
	v_med3_f32 v135, v135, s97, v226
	v_med3_f32 v136, v136, s97, v226
	v_med3_f32 v137, v137, s97, v226
	v_med3_f32 v138, v138, s97, v226
	v_med3_f32 v139, v139, s97, v226
	v_mul_f32_e32 v132, 0xbfb8aa3b, v132
	v_mul_f32_e32 v133, 0xbfb8aa3b, v133
	v_mul_f32_e32 v134, 0xbfb8aa3b, v134
	v_mul_f32_e32 v135, 0xbfb8aa3b, v135
	v_mul_f32_e32 v136, 0xbfb8aa3b, v136
	v_mul_f32_e32 v137, 0xbfb8aa3b, v137
	v_mul_f32_e32 v138, 0xbfb8aa3b, v138
	v_mul_f32_e32 v139, 0xbfb8aa3b, v139
	v_exp_f32_e32 v132, v132
	v_exp_f32_e32 v133, v133
	v_exp_f32_e32 v134, v134
	v_exp_f32_e32 v135, v135
	v_exp_f32_e32 v136, v136
	v_exp_f32_e32 v137, v137
	v_exp_f32_e32 v138, v138
	v_exp_f32_e32 v139, v139
	v_add_f32_e32 v132, 1.0, v132
	v_add_f32_e32 v133, 1.0, v133
	v_add_f32_e32 v134, 1.0, v134
	v_add_f32_e32 v135, 1.0, v135
	v_add_f32_e32 v136, 1.0, v136
	v_add_f32_e32 v137, 1.0, v137
	v_add_f32_e32 v138, 1.0, v138
	v_add_f32_e32 v139, 1.0, v139
	v_rcp_f32_e32 v132, v132
	v_rcp_f32_e32 v133, v133
	v_rcp_f32_e32 v134, v134
	v_rcp_f32_e32 v135, v135
	v_rcp_f32_e32 v136, v136
	v_rcp_f32_e32 v137, v137
	v_rcp_f32_e32 v138, v138
	v_rcp_f32_e32 v139, v139
	v_pk_mul_f32 v[132:133], v[8:9], v[132:133]
	v_pk_mul_f32 v[134:135], v[10:11], v[134:135]
	v_pk_mul_f32 v[136:137], v[4:5], v[136:137]
	v_pk_mul_f32 v[138:139], v[6:7], v[138:139]
	v_cvt_pk_bf16_f32 v248, v132, v133
	v_cvt_pk_bf16_f32 v249, v134, v135
	v_cvt_pk_bf16_f32 v250, v136, v137
	v_cvt_pk_bf16_f32 v251, v138, v139
	s_mov_b64 s[8:9], 0xb0000
	v_lshl_add_u64 v[156:157], v[154:155], 0, s[8:9]
	global_store_dwordx4 v[156:157], v[248:251], off offset:256
	s_mov_b64 s[40:41], 0
	s_mov_b64 s[42:43], -1
